# GEMM load segments: LDS-DMA stage loads (with address and M0 set-up) issued before the segment's ds_read_b128 fragment reads in P1/P4/P6/P7/P8 K-loops
# speedup vs baseline: 1.0040x; 1.0040x over previous
.LBB0_163:
	s_add_u32 s44, s8, 0xfffc0080
	s_addc_u32 s45, s9, -1
	s_cmp_eq_u32 s50, 12
	s_cselect_b32 s47, s5, s45
	s_cselect_b32 s46, s7, s44
	s_cselect_b32 s45, s37, s49
	s_cselect_b32 s44, s39, s48
	v_lshl_add_u64 v[222:223], s[8:9], 0, v[138:139]
	s_add_i32 m0, s20, 0xc000
	s_nop 0
	global_load_lds_dwordx4 v[222:223], off
	v_lshl_add_u64 v[222:223], s[8:9], 0, v[140:141]
	s_add_i32 m0, s20, 0xe000
	s_nop 0
	global_load_lds_dwordx4 v[222:223], off
	ds_read_b128 v[148:151], v155
	ds_read_b128 v[160:163], v155 offset:1024
	ds_read_b128 v[164:167], v155 offset:2048
	ds_read_b128 v[168:171], v155 offset:3072
	ds_read_b128 v[172:175], v156
	ds_read_b128 v[176:179], v156 offset:1024
	ds_read_b128 v[180:183], v156 offset:2048
	ds_read_b128 v[184:187], v156 offset:3072
	ds_read_b128 v[188:191], v157
	ds_read_b128 v[194:197], v157 offset:1024
	ds_read_b128 v[198:201], v157 offset:2048
	ds_read_b128 v[202:205], v157 offset:3072
	ds_read_b128 v[206:209], v157 offset:4096
	ds_read_b128 v[210:213], v157 offset:5120
	ds_read_b128 v[214:217], v157 offset:6144
	ds_read_b128 v[218:221], v157 offset:7168
	s_waitcnt vmcnt(8)
	s_waitcnt lgkmcnt(0)
	s_barrier
	s_setprio 1
	s_waitcnt lgkmcnt(0)
	v_mfma_f32_16x16x32_bf16 v[124:127], v[148:151], v[188:191], v[124:127]
	v_mfma_f32_16x16x32_bf16 v[120:123], v[164:167], v[188:191], v[120:123]
	v_mfma_f32_16x16x32_bf16 v[108:111], v[148:151], v[198:201], v[108:111]
	v_mfma_f32_16x16x32_bf16 v[104:107], v[164:167], v[198:201], v[104:107]
	v_mfma_f32_16x16x32_bf16 v[96:99], v[148:151], v[206:209], v[96:99]
	v_mfma_f32_16x16x32_bf16 v[88:91], v[164:167], v[206:209], v[88:91]
	v_mfma_f32_16x16x32_bf16 v[84:87], v[148:151], v[214:217], v[84:87]
	v_mfma_f32_16x16x32_bf16 v[76:79], v[164:167], v[214:217], v[76:79]
	v_mfma_f32_16x16x32_bf16 v[124:127], v[160:163], v[194:197], v[124:127]
	v_mfma_f32_16x16x32_bf16 v[120:123], v[168:171], v[194:197], v[120:123]
	v_mfma_f32_16x16x32_bf16 v[108:111], v[160:163], v[202:205], v[108:111]
	v_mfma_f32_16x16x32_bf16 v[104:107], v[168:171], v[202:205], v[104:107]
	v_mfma_f32_16x16x32_bf16 v[96:99], v[160:163], v[210:213], v[96:99]
	v_mfma_f32_16x16x32_bf16 v[88:91], v[168:171], v[210:213], v[88:91]
	v_mfma_f32_16x16x32_bf16 v[84:87], v[160:163], v[218:221], v[84:87]
	v_mfma_f32_16x16x32_bf16 v[76:79], v[168:171], v[218:221], v[76:79]
	s_setprio 0
	s_setprio 1
	v_mfma_f32_16x16x32_bf16 v[116:119], v[172:175], v[188:191], v[116:119]
	v_mfma_f32_16x16x32_bf16 v[112:115], v[180:183], v[188:191], v[112:115]
	v_mfma_f32_16x16x32_bf16 v[100:103], v[172:175], v[198:201], v[100:103]
	v_mfma_f32_16x16x32_bf16 v[92:95], v[180:183], v[198:201], v[92:95]
	v_mfma_f32_16x16x32_bf16 v[80:83], v[172:175], v[206:209], v[80:83]
	v_mfma_f32_16x16x32_bf16 v[72:75], v[180:183], v[206:209], v[72:75]
	v_mfma_f32_16x16x32_bf16 v[68:71], v[172:175], v[214:217], v[68:71]
	v_mfma_f32_16x16x32_bf16 v[64:67], v[180:183], v[214:217], v[64:67]
	v_mfma_f32_16x16x32_bf16 v[116:119], v[176:179], v[194:197], v[116:119]
	v_mfma_f32_16x16x32_bf16 v[112:115], v[184:187], v[194:197], v[112:115]
	v_mfma_f32_16x16x32_bf16 v[100:103], v[176:179], v[202:205], v[100:103]
	v_mfma_f32_16x16x32_bf16 v[92:95], v[184:187], v[202:205], v[92:95]
	v_mfma_f32_16x16x32_bf16 v[80:83], v[176:179], v[210:213], v[80:83]
	v_mfma_f32_16x16x32_bf16 v[72:75], v[184:187], v[210:213], v[72:75]
	v_mfma_f32_16x16x32_bf16 v[68:71], v[176:179], v[218:221], v[68:71]
	v_mfma_f32_16x16x32_bf16 v[64:67], v[184:187], v[218:221], v[64:67]
	s_setprio 0
	s_barrier
	s_add_i32 s51, s72, s15
	v_lshl_add_u64 v[222:223], s[44:45], 0, v[130:131]
	s_mov_b32 m0, s51
	global_load_lds_dwordx4 v[222:223], off
	s_add_i32 m0, s51, 0x2000
	s_add_u32 s64, s44, 0x40000
	v_lshl_add_u64 v[224:225], s[44:45], 0, v[134:135]
	s_addc_u32 s65, s45, 0
	s_add_i32 s51, s73, s15
	global_load_lds_dwordx4 v[224:225], off
	v_lshl_add_u64 v[226:227], s[64:65], 0, v[130:131]
	s_mov_b32 m0, s51
	v_lshl_add_u64 v[228:229], s[46:47], 0, v[132:133]
	global_load_lds_dwordx4 v[226:227], off
	v_lshl_add_u64 v[226:227], s[64:65], 0, v[134:135]
	s_add_i32 m0, s51, 0x2000
	s_nop 0
	global_load_lds_dwordx4 v[226:227], off
	v_lshl_add_u64 v[226:227], s[46:47], 0, v[128:129]
	s_mov_b32 m0, s20
	s_nop 0
	global_load_lds_dwordx4 v[226:227], off
	s_mov_b32 m0, s21
	s_nop 0
	global_load_lds_dwordx4 v[228:229], off
	ds_read_b128 v[188:191], v157 offset:16384
	ds_read_b128 v[194:197], v157 offset:17408
	ds_read_b128 v[198:201], v157 offset:18432
	ds_read_b128 v[202:205], v157 offset:19456
	ds_read_b128 v[206:209], v157 offset:20480
	ds_read_b128 v[210:213], v157 offset:21504
	ds_read_b128 v[214:217], v157 offset:22528
	ds_read_b128 v[218:221], v157 offset:23552
	s_waitcnt vmcnt(8)
	s_waitcnt lgkmcnt(0)
	s_barrier
	s_setprio 1
	s_waitcnt lgkmcnt(0)
	v_mfma_f32_16x16x32_bf16 v[60:63], v[148:151], v[188:191], v[60:63]
	v_mfma_f32_16x16x32_bf16 v[56:59], v[164:167], v[188:191], v[56:59]
	v_mfma_f32_16x16x32_bf16 v[44:47], v[148:151], v[198:201], v[44:47]
	v_mfma_f32_16x16x32_bf16 v[40:43], v[164:167], v[198:201], v[40:43]
	v_mfma_f32_16x16x32_bf16 v[32:35], v[148:151], v[206:209], v[32:35]
	v_mfma_f32_16x16x32_bf16 v[24:27], v[164:167], v[206:209], v[24:27]
	v_mfma_f32_16x16x32_bf16 v[20:23], v[148:151], v[214:217], v[20:23]
	v_mfma_f32_16x16x32_bf16 v[12:15], v[164:167], v[214:217], v[12:15]
	v_mfma_f32_16x16x32_bf16 v[60:63], v[160:163], v[194:197], v[60:63]
	v_mfma_f32_16x16x32_bf16 v[56:59], v[168:171], v[194:197], v[56:59]
	v_mfma_f32_16x16x32_bf16 v[44:47], v[160:163], v[202:205], v[44:47]
	v_mfma_f32_16x16x32_bf16 v[40:43], v[168:171], v[202:205], v[40:43]
	v_mfma_f32_16x16x32_bf16 v[32:35], v[160:163], v[210:213], v[32:35]
	v_mfma_f32_16x16x32_bf16 v[24:27], v[168:171], v[210:213], v[24:27]
	v_mfma_f32_16x16x32_bf16 v[20:23], v[160:163], v[218:221], v[20:23]
	v_mfma_f32_16x16x32_bf16 v[12:15], v[168:171], v[218:221], v[12:15]
	s_setprio 0
	s_setprio 1
	v_mfma_f32_16x16x32_bf16 v[52:55], v[172:175], v[188:191], v[52:55]
	v_mfma_f32_16x16x32_bf16 v[48:51], v[180:183], v[188:191], v[48:51]
	v_mfma_f32_16x16x32_bf16 v[36:39], v[172:175], v[198:201], v[36:39]
	v_mfma_f32_16x16x32_bf16 v[28:31], v[180:183], v[198:201], v[28:31]
	v_mfma_f32_16x16x32_bf16 v[16:19], v[172:175], v[206:209], v[16:19]
	v_mfma_f32_16x16x32_bf16 v[8:11], v[180:183], v[206:209], v[8:11]
	v_mfma_f32_16x16x32_bf16 v[4:7], v[172:175], v[214:217], v[4:7]
	v_mfma_f32_16x16x32_bf16 v[0:3], v[180:183], v[214:217], v[0:3]
	v_mfma_f32_16x16x32_bf16 v[52:55], v[176:179], v[194:197], v[52:55]
	v_mfma_f32_16x16x32_bf16 v[48:51], v[184:187], v[194:197], v[48:51]
	v_mfma_f32_16x16x32_bf16 v[36:39], v[176:179], v[202:205], v[36:39]
	v_mfma_f32_16x16x32_bf16 v[28:31], v[184:187], v[202:205], v[28:31]
	v_mfma_f32_16x16x32_bf16 v[16:19], v[176:179], v[210:213], v[16:19]
	v_mfma_f32_16x16x32_bf16 v[8:11], v[184:187], v[210:213], v[8:11]
	v_mfma_f32_16x16x32_bf16 v[4:7], v[176:179], v[218:221], v[4:7]
	v_mfma_f32_16x16x32_bf16 v[0:3], v[184:187], v[218:221], v[0:3]
	s_setprio 0
	s_barrier
	s_add_i32 s51, 0, 0x18000
	v_add_u32_e32 v136, s51, v154
	s_add_i32 s64, 0, 0x1c000
	ds_read_b128 v[148:151], v136
	ds_read_b128 v[160:163], v136 offset:1024
	ds_read_b128 v[164:167], v136 offset:2048
	ds_read_b128 v[168:171], v136 offset:3072
	v_add_u32_e32 v136, s64, v154
	ds_read_b128 v[172:175], v136
	ds_read_b128 v[176:179], v136 offset:1024
	ds_read_b128 v[180:183], v136 offset:2048
	ds_read_b128 v[184:187], v136 offset:3072
	s_add_u32 s46, s46, 0x40000
	s_addc_u32 s47, s47, 0
	s_mov_b32 m0, s22
	v_lshl_add_u64 v[230:231], s[46:47], 0, v[128:129]
	ds_read_b128 v[188:191], v157 offset:32768
	ds_read_b128 v[194:197], v157 offset:33792
	ds_read_b128 v[198:201], v157 offset:34816
	ds_read_b128 v[202:205], v157 offset:35840
	ds_read_b128 v[206:209], v157 offset:36864
	ds_read_b128 v[210:213], v157 offset:37888
	ds_read_b128 v[214:217], v157 offset:38912
	ds_read_b128 v[218:221], v157 offset:39936
	global_load_lds_dwordx4 v[230:231], off
	v_lshl_add_u64 v[230:231], s[46:47], 0, v[132:133]
	s_mov_b32 m0, s23
	s_nop 0
	global_load_lds_dwordx4 v[230:231], off
	s_waitcnt vmcnt(8)
	s_waitcnt lgkmcnt(0)
	s_barrier
	s_setprio 1
	s_waitcnt lgkmcnt(0)
	v_mfma_f32_16x16x32_bf16 v[124:127], v[148:151], v[188:191], v[124:127]
	v_mfma_f32_16x16x32_bf16 v[120:123], v[164:167], v[188:191], v[120:123]
	v_mfma_f32_16x16x32_bf16 v[108:111], v[148:151], v[198:201], v[108:111]
	v_mfma_f32_16x16x32_bf16 v[104:107], v[164:167], v[198:201], v[104:107]
	v_mfma_f32_16x16x32_bf16 v[96:99], v[148:151], v[206:209], v[96:99]
	v_mfma_f32_16x16x32_bf16 v[88:91], v[164:167], v[206:209], v[88:91]
	v_mfma_f32_16x16x32_bf16 v[84:87], v[148:151], v[214:217], v[84:87]
	v_mfma_f32_16x16x32_bf16 v[76:79], v[164:167], v[214:217], v[76:79]
	v_mfma_f32_16x16x32_bf16 v[124:127], v[160:163], v[194:197], v[124:127]
	v_mfma_f32_16x16x32_bf16 v[120:123], v[168:171], v[194:197], v[120:123]
	v_mfma_f32_16x16x32_bf16 v[108:111], v[160:163], v[202:205], v[108:111]
	v_mfma_f32_16x16x32_bf16 v[104:107], v[168:171], v[202:205], v[104:107]
	v_mfma_f32_16x16x32_bf16 v[96:99], v[160:163], v[210:213], v[96:99]
	v_mfma_f32_16x16x32_bf16 v[88:91], v[168:171], v[210:213], v[88:91]
	v_mfma_f32_16x16x32_bf16 v[84:87], v[160:163], v[218:221], v[84:87]
	v_mfma_f32_16x16x32_bf16 v[76:79], v[168:171], v[218:221], v[76:79]
	s_setprio 0
	s_setprio 1
	v_mfma_f32_16x16x32_bf16 v[116:119], v[172:175], v[188:191], v[116:119]
	v_mfma_f32_16x16x32_bf16 v[112:115], v[180:183], v[188:191], v[112:115]
	v_mfma_f32_16x16x32_bf16 v[100:103], v[172:175], v[198:201], v[100:103]
	v_mfma_f32_16x16x32_bf16 v[92:95], v[180:183], v[198:201], v[92:95]
	v_mfma_f32_16x16x32_bf16 v[80:83], v[172:175], v[206:209], v[80:83]
	v_mfma_f32_16x16x32_bf16 v[72:75], v[180:183], v[206:209], v[72:75]
	v_mfma_f32_16x16x32_bf16 v[68:71], v[172:175], v[214:217], v[68:71]
	v_mfma_f32_16x16x32_bf16 v[64:67], v[180:183], v[214:217], v[64:67]
	v_mfma_f32_16x16x32_bf16 v[116:119], v[176:179], v[194:197], v[116:119]
	v_mfma_f32_16x16x32_bf16 v[112:115], v[184:187], v[194:197], v[112:115]
	v_mfma_f32_16x16x32_bf16 v[100:103], v[176:179], v[202:205], v[100:103]
	v_mfma_f32_16x16x32_bf16 v[92:95], v[184:187], v[202:205], v[92:95]
	v_mfma_f32_16x16x32_bf16 v[80:83], v[176:179], v[210:213], v[80:83]
	v_mfma_f32_16x16x32_bf16 v[72:75], v[184:187], v[210:213], v[72:75]
	v_mfma_f32_16x16x32_bf16 v[68:71], v[176:179], v[218:221], v[68:71]
	v_mfma_f32_16x16x32_bf16 v[64:67], v[184:187], v[218:221], v[64:67]
	s_setprio 0
	s_barrier
	s_add_i32 s46, s51, s15
	v_lshl_add_u64 v[222:223], v[222:223], 0, s[18:19]
	s_mov_b32 m0, s46
	global_load_lds_dwordx4 v[222:223], off
	s_add_i32 m0, s46, 0x2000
	s_add_u32 s44, s44, 0x40080
	v_lshl_add_u64 v[222:223], v[224:225], 0, s[18:19]
	s_addc_u32 s45, s45, 0
	s_add_i32 s46, s64, s15
	global_load_lds_dwordx4 v[222:223], off
	v_lshl_add_u64 v[222:223], s[44:45], 0, v[130:131]
	s_mov_b32 m0, s46
	s_nop 0
	global_load_lds_dwordx4 v[222:223], off
	v_lshl_add_u64 v[222:223], s[44:45], 0, v[134:135]
	s_add_i32 m0, s46, 0x2000
	s_nop 0
	global_load_lds_dwordx4 v[222:223], off
	v_lshl_add_u64 v[222:223], v[226:227], 0, s[18:19]
	s_mov_b32 m0, s70
	s_nop 0
	global_load_lds_dwordx4 v[222:223], off
	v_lshl_add_u64 v[222:223], v[228:229], 0, s[18:19]
	s_mov_b32 m0, s71
	s_nop 0
	global_load_lds_dwordx4 v[222:223], off
	ds_read_b128 v[188:191], v157 offset:49152
	ds_read_b128 v[194:197], v157 offset:50176
	ds_read_b128 v[198:201], v157 offset:51200
	ds_read_b128 v[202:205], v157 offset:52224
	ds_read_b128 v[206:209], v157 offset:53248
	ds_read_b128 v[210:213], v157 offset:54272
	ds_read_b128 v[214:217], v157 offset:55296
	ds_read_b128 v[218:221], v157 offset:56320
	s_waitcnt vmcnt(8)
	s_waitcnt lgkmcnt(0)
	s_barrier
	s_setprio 1
	s_waitcnt lgkmcnt(0)
	v_mfma_f32_16x16x32_bf16 v[60:63], v[148:151], v[188:191], v[60:63]
	v_mfma_f32_16x16x32_bf16 v[56:59], v[164:167], v[188:191], v[56:59]
	v_mfma_f32_16x16x32_bf16 v[44:47], v[148:151], v[198:201], v[44:47]
	v_mfma_f32_16x16x32_bf16 v[40:43], v[164:167], v[198:201], v[40:43]
	v_mfma_f32_16x16x32_bf16 v[32:35], v[148:151], v[206:209], v[32:35]
	v_mfma_f32_16x16x32_bf16 v[24:27], v[164:167], v[206:209], v[24:27]
	v_mfma_f32_16x16x32_bf16 v[20:23], v[148:151], v[214:217], v[20:23]
	v_mfma_f32_16x16x32_bf16 v[12:15], v[164:167], v[214:217], v[12:15]
	v_mfma_f32_16x16x32_bf16 v[60:63], v[160:163], v[194:197], v[60:63]
	v_mfma_f32_16x16x32_bf16 v[56:59], v[168:171], v[194:197], v[56:59]
	v_mfma_f32_16x16x32_bf16 v[44:47], v[160:163], v[202:205], v[44:47]
	v_mfma_f32_16x16x32_bf16 v[40:43], v[168:171], v[202:205], v[40:43]
	v_mfma_f32_16x16x32_bf16 v[32:35], v[160:163], v[210:213], v[32:35]
	v_mfma_f32_16x16x32_bf16 v[24:27], v[168:171], v[210:213], v[24:27]
	v_mfma_f32_16x16x32_bf16 v[20:23], v[160:163], v[218:221], v[20:23]
	v_mfma_f32_16x16x32_bf16 v[12:15], v[168:171], v[218:221], v[12:15]
	s_setprio 0
	s_setprio 1
	v_mfma_f32_16x16x32_bf16 v[52:55], v[172:175], v[188:191], v[52:55]
	v_mfma_f32_16x16x32_bf16 v[48:51], v[180:183], v[188:191], v[48:51]
	v_mfma_f32_16x16x32_bf16 v[36:39], v[172:175], v[198:201], v[36:39]
	v_mfma_f32_16x16x32_bf16 v[28:31], v[180:183], v[198:201], v[28:31]
	v_mfma_f32_16x16x32_bf16 v[16:19], v[172:175], v[206:209], v[16:19]
	v_mfma_f32_16x16x32_bf16 v[8:11], v[180:183], v[206:209], v[8:11]
	v_mfma_f32_16x16x32_bf16 v[4:7], v[172:175], v[214:217], v[4:7]
	v_mfma_f32_16x16x32_bf16 v[0:3], v[180:183], v[214:217], v[0:3]
	v_mfma_f32_16x16x32_bf16 v[52:55], v[176:179], v[194:197], v[52:55]
	v_mfma_f32_16x16x32_bf16 v[48:51], v[184:187], v[194:197], v[48:51]
	v_mfma_f32_16x16x32_bf16 v[36:39], v[176:179], v[202:205], v[36:39]
	v_mfma_f32_16x16x32_bf16 v[28:31], v[184:187], v[202:205], v[28:31]
	v_mfma_f32_16x16x32_bf16 v[16:19], v[176:179], v[210:213], v[16:19]
	v_mfma_f32_16x16x32_bf16 v[8:11], v[184:187], v[210:213], v[8:11]
	v_mfma_f32_16x16x32_bf16 v[4:7], v[176:179], v[218:221], v[4:7]
	v_mfma_f32_16x16x32_bf16 v[0:3], v[184:187], v[218:221], v[0:3]
	s_setprio 0
	s_barrier
	s_add_i32 s50, s50, 2
	s_add_u32 s8, s8, 0x100
	s_addc_u32 s9, s9, 0
	s_add_u32 s48, s48, 0x100
	s_addc_u32 s49, s49, 0
	s_cmp_gt_u32 s50, 13
	s_cbranch_scc0 .LBB0_163
	s_and_b64 vcc, exec, s[34:35]
	s_cbranch_vccz .LBB0_166
	s_barrier

.LBB0_640:
	s_add_u32 s42, s36, 0xfffc0080
	s_addc_u32 s43, s37, -1
	s_cmp_eq_u32 s71, 12
	s_cselect_b32 s47, s13, s43
	s_cselect_b32 s46, s67, s42
	s_cselect_b32 s43, s11, s70
	s_cselect_b32 s42, s68, s69
	v_lshl_add_u64 v[148:149], s[36:37], 0, v[138:139]
	s_add_i32 m0, s22, 0xc000
	s_nop 0
	global_load_lds_dwordx4 v[148:149], off
	v_lshl_add_u64 v[148:149], s[36:37], 0, v[140:141]
	s_add_i32 m0, s22, 0xe000
	s_nop 0
	global_load_lds_dwordx4 v[148:149], off
	ds_read_b128 v[170:173], v164
	ds_read_b128 v[174:177], v164 offset:1024
	ds_read_b128 v[178:181], v164 offset:2048
	ds_read_b128 v[182:185], v164 offset:3072
	ds_read_b128 v[186:189], v165
	ds_read_b128 v[194:197], v165 offset:1024
	ds_read_b128 v[198:201], v165 offset:2048
	ds_read_b128 v[202:205], v165 offset:3072
	ds_read_b128 v[206:209], v166
	ds_read_b128 v[210:213], v166 offset:1024
	ds_read_b128 v[214:217], v166 offset:2048
	ds_read_b128 v[218:221], v166 offset:3072
	ds_read_b128 v[222:225], v166 offset:4096
	ds_read_b128 v[226:229], v166 offset:5120
	ds_read_b128 v[230:233], v166 offset:6144
	ds_read_b128 v[234:237], v166 offset:7168
	s_waitcnt vmcnt(8)
	s_waitcnt lgkmcnt(0)
	s_barrier
	s_setprio 1
	s_waitcnt lgkmcnt(0)
	v_mfma_f32_16x16x32_bf16 v[124:127], v[170:173], v[206:209], v[124:127]
	v_mfma_f32_16x16x32_bf16 v[120:123], v[178:181], v[206:209], v[120:123]
	v_mfma_f32_16x16x32_bf16 v[116:119], v[170:173], v[214:217], v[116:119]
	v_mfma_f32_16x16x32_bf16 v[112:115], v[178:181], v[214:217], v[112:115]
	v_mfma_f32_16x16x32_bf16 v[100:103], v[170:173], v[222:225], v[100:103]
	v_mfma_f32_16x16x32_bf16 v[96:99], v[178:181], v[222:225], v[96:99]
	v_mfma_f32_16x16x32_bf16 v[84:87], v[170:173], v[230:233], v[84:87]
	v_mfma_f32_16x16x32_bf16 v[80:83], v[178:181], v[230:233], v[80:83]
	v_mfma_f32_16x16x32_bf16 v[124:127], v[174:177], v[210:213], v[124:127]
	v_mfma_f32_16x16x32_bf16 v[120:123], v[182:185], v[210:213], v[120:123]
	v_mfma_f32_16x16x32_bf16 v[116:119], v[174:177], v[218:221], v[116:119]
	v_mfma_f32_16x16x32_bf16 v[112:115], v[182:185], v[218:221], v[112:115]
	v_mfma_f32_16x16x32_bf16 v[100:103], v[174:177], v[226:229], v[100:103]
	v_mfma_f32_16x16x32_bf16 v[96:99], v[182:185], v[226:229], v[96:99]
	v_mfma_f32_16x16x32_bf16 v[84:87], v[174:177], v[234:237], v[84:87]
	v_mfma_f32_16x16x32_bf16 v[80:83], v[182:185], v[234:237], v[80:83]
	s_setprio 0
	s_setprio 1
	v_mfma_f32_16x16x32_bf16 v[108:111], v[186:189], v[206:209], v[108:111]
	v_mfma_f32_16x16x32_bf16 v[104:107], v[198:201], v[206:209], v[104:107]
	v_mfma_f32_16x16x32_bf16 v[92:95], v[186:189], v[214:217], v[92:95]
	v_mfma_f32_16x16x32_bf16 v[88:91], v[198:201], v[214:217], v[88:91]
	v_mfma_f32_16x16x32_bf16 v[76:79], v[186:189], v[222:225], v[76:79]
	v_mfma_f32_16x16x32_bf16 v[72:75], v[198:201], v[222:225], v[72:75]
	v_mfma_f32_16x16x32_bf16 v[68:71], v[186:189], v[230:233], v[68:71]
	v_mfma_f32_16x16x32_bf16 v[64:67], v[198:201], v[230:233], v[64:67]
	v_mfma_f32_16x16x32_bf16 v[108:111], v[194:197], v[210:213], v[108:111]
	v_mfma_f32_16x16x32_bf16 v[104:107], v[202:205], v[210:213], v[104:107]
	v_mfma_f32_16x16x32_bf16 v[92:95], v[194:197], v[218:221], v[92:95]
	v_mfma_f32_16x16x32_bf16 v[88:91], v[202:205], v[218:221], v[88:91]
	v_mfma_f32_16x16x32_bf16 v[76:79], v[194:197], v[226:229], v[76:79]
	v_mfma_f32_16x16x32_bf16 v[72:75], v[202:205], v[226:229], v[72:75]
	v_mfma_f32_16x16x32_bf16 v[68:71], v[194:197], v[234:237], v[68:71]
	v_mfma_f32_16x16x32_bf16 v[64:67], v[202:205], v[234:237], v[64:67]
	s_setprio 0
	s_barrier
	s_add_i32 s72, s65, s14
	v_lshl_add_u64 v[148:149], s[42:43], 0, v[132:133]
	s_mov_b32 m0, s72
	global_load_lds_dwordx4 v[148:149], off
	s_add_i32 m0, s72, 0x2000
	s_add_u32 s72, s42, 0x40000
	v_lshl_add_u64 v[190:191], s[42:43], 0, v[128:129]
	s_addc_u32 s73, s43, 0
	s_add_i32 s78, s66, s14
	global_load_lds_dwordx4 v[190:191], off
	v_lshl_add_u64 v[238:239], s[72:73], 0, v[132:133]
	s_mov_b32 m0, s78
	v_lshl_add_u64 v[240:241], s[46:47], 0, v[130:131]
	global_load_lds_dwordx4 v[238:239], off
	v_lshl_add_u64 v[238:239], s[72:73], 0, v[128:129]
	s_add_i32 m0, s78, 0x2000
	s_nop 0
	global_load_lds_dwordx4 v[238:239], off
	v_lshl_add_u64 v[238:239], s[46:47], 0, v[134:135]
	s_mov_b32 m0, s22
	s_nop 0
	global_load_lds_dwordx4 v[238:239], off
	s_mov_b32 m0, s23
	s_nop 0
	global_load_lds_dwordx4 v[240:241], off
	ds_read_b128 v[206:209], v166 offset:16384
	ds_read_b128 v[210:213], v166 offset:17408
	ds_read_b128 v[214:217], v166 offset:18432
	ds_read_b128 v[218:221], v166 offset:19456
	ds_read_b128 v[222:225], v166 offset:20480
	ds_read_b128 v[226:229], v166 offset:21504
	ds_read_b128 v[230:233], v166 offset:22528
	ds_read_b128 v[234:237], v166 offset:23552
	s_waitcnt vmcnt(8)
	s_waitcnt lgkmcnt(0)
	s_barrier
	s_setprio 1
	s_waitcnt lgkmcnt(0)
	v_mfma_f32_16x16x32_bf16 v[60:63], v[170:173], v[206:209], v[60:63]
	v_mfma_f32_16x16x32_bf16 v[56:59], v[178:181], v[206:209], v[56:59]
	v_mfma_f32_16x16x32_bf16 v[52:55], v[170:173], v[214:217], v[52:55]
	v_mfma_f32_16x16x32_bf16 v[48:51], v[178:181], v[214:217], v[48:51]
	v_mfma_f32_16x16x32_bf16 v[36:39], v[170:173], v[222:225], v[36:39]
	v_mfma_f32_16x16x32_bf16 v[32:35], v[178:181], v[222:225], v[32:35]
	v_mfma_f32_16x16x32_bf16 v[20:23], v[170:173], v[230:233], v[20:23]
	v_mfma_f32_16x16x32_bf16 v[16:19], v[178:181], v[230:233], v[16:19]
	v_mfma_f32_16x16x32_bf16 v[60:63], v[174:177], v[210:213], v[60:63]
	v_mfma_f32_16x16x32_bf16 v[56:59], v[182:185], v[210:213], v[56:59]
	v_mfma_f32_16x16x32_bf16 v[52:55], v[174:177], v[218:221], v[52:55]
	v_mfma_f32_16x16x32_bf16 v[48:51], v[182:185], v[218:221], v[48:51]
	v_mfma_f32_16x16x32_bf16 v[36:39], v[174:177], v[226:229], v[36:39]
	v_mfma_f32_16x16x32_bf16 v[32:35], v[182:185], v[226:229], v[32:35]
	v_mfma_f32_16x16x32_bf16 v[20:23], v[174:177], v[234:237], v[20:23]
	v_mfma_f32_16x16x32_bf16 v[16:19], v[182:185], v[234:237], v[16:19]
	s_setprio 0
	s_setprio 1
	v_mfma_f32_16x16x32_bf16 v[44:47], v[186:189], v[206:209], v[44:47]
	v_mfma_f32_16x16x32_bf16 v[40:43], v[198:201], v[206:209], v[40:43]
	v_mfma_f32_16x16x32_bf16 v[28:31], v[186:189], v[214:217], v[28:31]
	v_mfma_f32_16x16x32_bf16 v[24:27], v[198:201], v[214:217], v[24:27]
	v_mfma_f32_16x16x32_bf16 v[12:15], v[186:189], v[222:225], v[12:15]
	v_mfma_f32_16x16x32_bf16 v[8:11], v[198:201], v[222:225], v[8:11]
	v_mfma_f32_16x16x32_bf16 v[4:7], v[186:189], v[230:233], v[4:7]
	v_mfma_f32_16x16x32_bf16 v[0:3], v[198:201], v[230:233], v[0:3]
	v_mfma_f32_16x16x32_bf16 v[44:47], v[194:197], v[210:213], v[44:47]
	v_mfma_f32_16x16x32_bf16 v[40:43], v[202:205], v[210:213], v[40:43]
	v_mfma_f32_16x16x32_bf16 v[28:31], v[194:197], v[218:221], v[28:31]
	v_mfma_f32_16x16x32_bf16 v[24:27], v[202:205], v[218:221], v[24:27]
	v_mfma_f32_16x16x32_bf16 v[12:15], v[194:197], v[226:229], v[12:15]
	v_mfma_f32_16x16x32_bf16 v[8:11], v[202:205], v[226:229], v[8:11]
	v_mfma_f32_16x16x32_bf16 v[4:7], v[194:197], v[234:237], v[4:7]
	v_mfma_f32_16x16x32_bf16 v[0:3], v[202:205], v[234:237], v[0:3]
	s_setprio 0
	s_barrier
	s_add_i32 s72, 0, 0x18000
	v_add_u32_e32 v136, s72, v152
	s_add_i32 s73, 0, 0x1c000
	ds_read_b128 v[170:173], v136
	ds_read_b128 v[174:177], v136 offset:1024
	ds_read_b128 v[178:181], v136 offset:2048
	ds_read_b128 v[182:185], v136 offset:3072
	v_add_u32_e32 v136, s73, v152
	ds_read_b128 v[186:189], v136
	ds_read_b128 v[194:197], v136 offset:1024
	ds_read_b128 v[198:201], v136 offset:2048
	ds_read_b128 v[202:205], v136 offset:3072
	s_add_u32 s46, s46, 0x40000
	s_addc_u32 s47, s47, 0
	s_mov_b32 m0, s33
	v_lshl_add_u64 v[242:243], s[46:47], 0, v[134:135]
	ds_read_b128 v[206:209], v166 offset:32768
	ds_read_b128 v[210:213], v166 offset:33792
	ds_read_b128 v[214:217], v166 offset:34816
	ds_read_b128 v[218:221], v166 offset:35840
	ds_read_b128 v[222:225], v166 offset:36864
	ds_read_b128 v[226:229], v166 offset:37888
	ds_read_b128 v[230:233], v166 offset:38912
	ds_read_b128 v[234:237], v166 offset:39936
	global_load_lds_dwordx4 v[242:243], off
	v_lshl_add_u64 v[242:243], s[46:47], 0, v[130:131]
	s_mov_b32 m0, s48
	s_nop 0
	global_load_lds_dwordx4 v[242:243], off
	s_waitcnt vmcnt(8)
	s_waitcnt lgkmcnt(0)
	s_barrier
	s_setprio 1
	s_waitcnt lgkmcnt(0)
	v_mfma_f32_16x16x32_bf16 v[124:127], v[170:173], v[206:209], v[124:127]
	v_mfma_f32_16x16x32_bf16 v[120:123], v[178:181], v[206:209], v[120:123]
	v_mfma_f32_16x16x32_bf16 v[116:119], v[170:173], v[214:217], v[116:119]
	v_mfma_f32_16x16x32_bf16 v[112:115], v[178:181], v[214:217], v[112:115]
	v_mfma_f32_16x16x32_bf16 v[100:103], v[170:173], v[222:225], v[100:103]
	v_mfma_f32_16x16x32_bf16 v[96:99], v[178:181], v[222:225], v[96:99]
	v_mfma_f32_16x16x32_bf16 v[84:87], v[170:173], v[230:233], v[84:87]
	v_mfma_f32_16x16x32_bf16 v[80:83], v[178:181], v[230:233], v[80:83]
	v_mfma_f32_16x16x32_bf16 v[124:127], v[174:177], v[210:213], v[124:127]
	v_mfma_f32_16x16x32_bf16 v[120:123], v[182:185], v[210:213], v[120:123]
	v_mfma_f32_16x16x32_bf16 v[116:119], v[174:177], v[218:221], v[116:119]
	v_mfma_f32_16x16x32_bf16 v[112:115], v[182:185], v[218:221], v[112:115]
	v_mfma_f32_16x16x32_bf16 v[100:103], v[174:177], v[226:229], v[100:103]
	v_mfma_f32_16x16x32_bf16 v[96:99], v[182:185], v[226:229], v[96:99]
	v_mfma_f32_16x16x32_bf16 v[84:87], v[174:177], v[234:237], v[84:87]
	v_mfma_f32_16x16x32_bf16 v[80:83], v[182:185], v[234:237], v[80:83]
	s_setprio 0
	s_setprio 1
	v_mfma_f32_16x16x32_bf16 v[108:111], v[186:189], v[206:209], v[108:111]
	v_mfma_f32_16x16x32_bf16 v[104:107], v[198:201], v[206:209], v[104:107]
	v_mfma_f32_16x16x32_bf16 v[92:95], v[186:189], v[214:217], v[92:95]
	v_mfma_f32_16x16x32_bf16 v[88:91], v[198:201], v[214:217], v[88:91]
	v_mfma_f32_16x16x32_bf16 v[76:79], v[186:189], v[222:225], v[76:79]
	v_mfma_f32_16x16x32_bf16 v[72:75], v[198:201], v[222:225], v[72:75]
	v_mfma_f32_16x16x32_bf16 v[68:71], v[186:189], v[230:233], v[68:71]
	v_mfma_f32_16x16x32_bf16 v[64:67], v[198:201], v[230:233], v[64:67]
	v_mfma_f32_16x16x32_bf16 v[108:111], v[194:197], v[210:213], v[108:111]
	v_mfma_f32_16x16x32_bf16 v[104:107], v[202:205], v[210:213], v[104:107]
	v_mfma_f32_16x16x32_bf16 v[92:95], v[194:197], v[218:221], v[92:95]
	v_mfma_f32_16x16x32_bf16 v[88:91], v[202:205], v[218:221], v[88:91]
	v_mfma_f32_16x16x32_bf16 v[76:79], v[194:197], v[226:229], v[76:79]
	v_mfma_f32_16x16x32_bf16 v[72:75], v[202:205], v[226:229], v[72:75]
	v_mfma_f32_16x16x32_bf16 v[68:71], v[194:197], v[234:237], v[68:71]
	v_mfma_f32_16x16x32_bf16 v[64:67], v[202:205], v[234:237], v[64:67]
	s_setprio 0
	s_barrier
	s_add_i32 s46, s72, s14
	v_lshl_add_u64 v[148:149], v[148:149], 0, s[4:5]
	s_mov_b32 m0, s46
	global_load_lds_dwordx4 v[148:149], off
	s_add_i32 m0, s46, 0x2000
	s_add_u32 s42, s42, 0x40080
	v_lshl_add_u64 v[148:149], v[190:191], 0, s[4:5]
	s_addc_u32 s43, s43, 0
	s_add_i32 s46, s73, s14
	global_load_lds_dwordx4 v[148:149], off
	v_lshl_add_u64 v[148:149], s[42:43], 0, v[132:133]
	s_mov_b32 m0, s46
	s_nop 0
	global_load_lds_dwordx4 v[148:149], off
	v_lshl_add_u64 v[148:149], s[42:43], 0, v[128:129]
	s_add_i32 m0, s46, 0x2000
	s_nop 0
	global_load_lds_dwordx4 v[148:149], off
	v_lshl_add_u64 v[148:149], v[238:239], 0, s[4:5]
	s_mov_b32 m0, s50
	s_nop 0
	global_load_lds_dwordx4 v[148:149], off
	v_lshl_add_u64 v[148:149], v[240:241], 0, s[4:5]
	s_mov_b32 m0, s51
	s_nop 0
	global_load_lds_dwordx4 v[148:149], off
	ds_read_b128 v[206:209], v166 offset:49152
	ds_read_b128 v[210:213], v166 offset:50176
	ds_read_b128 v[214:217], v166 offset:51200
	ds_read_b128 v[218:221], v166 offset:52224
	ds_read_b128 v[222:225], v166 offset:53248
	ds_read_b128 v[226:229], v166 offset:54272
	ds_read_b128 v[230:233], v166 offset:55296
	ds_read_b128 v[234:237], v166 offset:56320
	s_waitcnt vmcnt(8)
	s_waitcnt lgkmcnt(0)
	s_barrier
	s_setprio 1
	s_waitcnt lgkmcnt(0)
	v_mfma_f32_16x16x32_bf16 v[60:63], v[170:173], v[206:209], v[60:63]
	v_mfma_f32_16x16x32_bf16 v[56:59], v[178:181], v[206:209], v[56:59]
	v_mfma_f32_16x16x32_bf16 v[52:55], v[170:173], v[214:217], v[52:55]
	v_mfma_f32_16x16x32_bf16 v[48:51], v[178:181], v[214:217], v[48:51]
	v_mfma_f32_16x16x32_bf16 v[36:39], v[170:173], v[222:225], v[36:39]
	v_mfma_f32_16x16x32_bf16 v[32:35], v[178:181], v[222:225], v[32:35]
	v_mfma_f32_16x16x32_bf16 v[20:23], v[170:173], v[230:233], v[20:23]
	v_mfma_f32_16x16x32_bf16 v[16:19], v[178:181], v[230:233], v[16:19]
	v_mfma_f32_16x16x32_bf16 v[60:63], v[174:177], v[210:213], v[60:63]
	v_mfma_f32_16x16x32_bf16 v[56:59], v[182:185], v[210:213], v[56:59]
	v_mfma_f32_16x16x32_bf16 v[52:55], v[174:177], v[218:221], v[52:55]
	v_mfma_f32_16x16x32_bf16 v[48:51], v[182:185], v[218:221], v[48:51]
	v_mfma_f32_16x16x32_bf16 v[36:39], v[174:177], v[226:229], v[36:39]
	v_mfma_f32_16x16x32_bf16 v[32:35], v[182:185], v[226:229], v[32:35]
	v_mfma_f32_16x16x32_bf16 v[20:23], v[174:177], v[234:237], v[20:23]
	v_mfma_f32_16x16x32_bf16 v[16:19], v[182:185], v[234:237], v[16:19]
	s_setprio 0
	s_setprio 1
	v_mfma_f32_16x16x32_bf16 v[44:47], v[186:189], v[206:209], v[44:47]
	v_mfma_f32_16x16x32_bf16 v[40:43], v[198:201], v[206:209], v[40:43]
	v_mfma_f32_16x16x32_bf16 v[28:31], v[186:189], v[214:217], v[28:31]
	v_mfma_f32_16x16x32_bf16 v[24:27], v[198:201], v[214:217], v[24:27]
	v_mfma_f32_16x16x32_bf16 v[12:15], v[186:189], v[222:225], v[12:15]
	v_mfma_f32_16x16x32_bf16 v[8:11], v[198:201], v[222:225], v[8:11]
	v_mfma_f32_16x16x32_bf16 v[4:7], v[186:189], v[230:233], v[4:7]
	v_mfma_f32_16x16x32_bf16 v[0:3], v[198:201], v[230:233], v[0:3]
	v_mfma_f32_16x16x32_bf16 v[44:47], v[194:197], v[210:213], v[44:47]
	v_mfma_f32_16x16x32_bf16 v[40:43], v[202:205], v[210:213], v[40:43]
	v_mfma_f32_16x16x32_bf16 v[28:31], v[194:197], v[218:221], v[28:31]
	v_mfma_f32_16x16x32_bf16 v[24:27], v[202:205], v[218:221], v[24:27]
	v_mfma_f32_16x16x32_bf16 v[12:15], v[194:197], v[226:229], v[12:15]
	v_mfma_f32_16x16x32_bf16 v[8:11], v[202:205], v[226:229], v[8:11]
	v_mfma_f32_16x16x32_bf16 v[4:7], v[194:197], v[234:237], v[4:7]
	v_mfma_f32_16x16x32_bf16 v[0:3], v[202:205], v[234:237], v[0:3]
	s_setprio 0
	s_barrier
	s_add_i32 s71, s71, 2
	s_add_u32 s36, s36, 0x100
	s_addc_u32 s37, s37, 0
	s_add_u32 s69, s69, 0x100
	s_addc_u32 s70, s70, 0
	s_cmp_gt_u32 s71, 13
	s_cbranch_scc0 .LBB0_640
	s_and_b64 vcc, exec, s[6:7]
	s_cbranch_vccz .LBB0_643
	s_barrier

.LBB0_677:
	s_add_u32 s42, s36, 0xfffc0080
	s_addc_u32 s43, s37, -1
	s_cmp_eq_u32 s67, 12
	s_cselect_b32 s47, s13, s43
	s_cselect_b32 s46, s53, s42
	s_cselect_b32 s43, s11, s66
	s_cselect_b32 s42, s64, s65
	v_lshl_add_u64 v[190:191], s[36:37], 0, v[136:137]
	s_add_i32 m0, s21, 0xc000
	s_nop 0
	global_load_lds_dwordx4 v[190:191], off
	v_lshl_add_u64 v[190:191], s[36:37], 0, v[138:139]
	s_add_i32 m0, s21, 0xe000
	s_nop 0
	global_load_lds_dwordx4 v[190:191], off
	ds_read_b128 v[150:153], v147
	ds_read_b128 v[154:157], v147 offset:1024
	ds_read_b128 v[158:161], v147 offset:2048
	ds_read_b128 v[162:165], v147 offset:3072
	ds_read_b128 v[166:169], v148
	ds_read_b128 v[170:173], v148 offset:1024
	ds_read_b128 v[174:177], v148 offset:2048
	ds_read_b128 v[178:181], v148 offset:3072
	ds_read_b128 v[182:185], v149
	ds_read_b128 v[186:189], v149 offset:1024
	ds_read_b128 v[194:197], v149 offset:2048
	ds_read_b128 v[198:201], v149 offset:3072
	ds_read_b128 v[202:205], v149 offset:4096
	ds_read_b128 v[206:209], v149 offset:5120
	ds_read_b128 v[210:213], v149 offset:6144
	ds_read_b128 v[214:217], v149 offset:7168
	s_waitcnt vmcnt(8)
	s_waitcnt lgkmcnt(0)
	s_barrier
	s_setprio 1
	s_waitcnt lgkmcnt(0)
	v_mfma_f32_16x16x32_bf16 v[124:127], v[150:153], v[182:185], v[124:127]
	v_mfma_f32_16x16x32_bf16 v[120:123], v[158:161], v[182:185], v[120:123]
	v_mfma_f32_16x16x32_bf16 v[116:119], v[150:153], v[194:197], v[116:119]
	v_mfma_f32_16x16x32_bf16 v[112:115], v[158:161], v[194:197], v[112:115]
	v_mfma_f32_16x16x32_bf16 v[100:103], v[150:153], v[202:205], v[100:103]
	v_mfma_f32_16x16x32_bf16 v[96:99], v[158:161], v[202:205], v[96:99]
	v_mfma_f32_16x16x32_bf16 v[84:87], v[150:153], v[210:213], v[84:87]
	v_mfma_f32_16x16x32_bf16 v[80:83], v[158:161], v[210:213], v[80:83]
	v_mfma_f32_16x16x32_bf16 v[124:127], v[154:157], v[186:189], v[124:127]
	v_mfma_f32_16x16x32_bf16 v[120:123], v[162:165], v[186:189], v[120:123]
	v_mfma_f32_16x16x32_bf16 v[116:119], v[154:157], v[198:201], v[116:119]
	v_mfma_f32_16x16x32_bf16 v[112:115], v[162:165], v[198:201], v[112:115]
	v_mfma_f32_16x16x32_bf16 v[100:103], v[154:157], v[206:209], v[100:103]
	v_mfma_f32_16x16x32_bf16 v[96:99], v[162:165], v[206:209], v[96:99]
	v_mfma_f32_16x16x32_bf16 v[84:87], v[154:157], v[214:217], v[84:87]
	v_mfma_f32_16x16x32_bf16 v[80:83], v[162:165], v[214:217], v[80:83]
	s_setprio 0
	s_setprio 1
	v_mfma_f32_16x16x32_bf16 v[108:111], v[166:169], v[182:185], v[108:111]
	v_mfma_f32_16x16x32_bf16 v[104:107], v[174:177], v[182:185], v[104:107]
	v_mfma_f32_16x16x32_bf16 v[92:95], v[166:169], v[194:197], v[92:95]
	v_mfma_f32_16x16x32_bf16 v[88:91], v[174:177], v[194:197], v[88:91]
	v_mfma_f32_16x16x32_bf16 v[76:79], v[166:169], v[202:205], v[76:79]
	v_mfma_f32_16x16x32_bf16 v[72:75], v[174:177], v[202:205], v[72:75]
	v_mfma_f32_16x16x32_bf16 v[68:71], v[166:169], v[210:213], v[68:71]
	v_mfma_f32_16x16x32_bf16 v[64:67], v[174:177], v[210:213], v[64:67]
	v_mfma_f32_16x16x32_bf16 v[108:111], v[170:173], v[186:189], v[108:111]
	v_mfma_f32_16x16x32_bf16 v[104:107], v[178:181], v[186:189], v[104:107]
	v_mfma_f32_16x16x32_bf16 v[92:95], v[170:173], v[198:201], v[92:95]
	v_mfma_f32_16x16x32_bf16 v[88:91], v[178:181], v[198:201], v[88:91]
	v_mfma_f32_16x16x32_bf16 v[76:79], v[170:173], v[206:209], v[76:79]
	v_mfma_f32_16x16x32_bf16 v[72:75], v[178:181], v[206:209], v[72:75]
	v_mfma_f32_16x16x32_bf16 v[68:71], v[170:173], v[214:217], v[68:71]
	v_mfma_f32_16x16x32_bf16 v[64:67], v[178:181], v[214:217], v[64:67]
	s_setprio 0
	s_barrier
	s_add_i32 s68, s51, s14
	v_lshl_add_u64 v[190:191], s[42:43], 0, v[132:133]
	s_mov_b32 m0, s68
	global_load_lds_dwordx4 v[190:191], off
	s_add_i32 m0, s68, 0x2000
	s_add_u32 s68, s42, 0x40000
	v_lshl_add_u64 v[218:219], s[42:43], 0, v[128:129]
	s_addc_u32 s69, s43, 0
	s_add_i32 s70, s52, s14
	global_load_lds_dwordx4 v[218:219], off
	v_lshl_add_u64 v[220:221], s[68:69], 0, v[132:133]
	s_mov_b32 m0, s70
	v_lshl_add_u64 v[222:223], s[46:47], 0, v[130:131]
	global_load_lds_dwordx4 v[220:221], off
	v_lshl_add_u64 v[220:221], s[68:69], 0, v[128:129]
	s_add_i32 m0, s70, 0x2000
	s_nop 0
	global_load_lds_dwordx4 v[220:221], off
	v_lshl_add_u64 v[220:221], s[46:47], 0, v[134:135]
	s_mov_b32 m0, s21
	s_nop 0
	global_load_lds_dwordx4 v[220:221], off
	s_mov_b32 m0, s22
	s_nop 0
	global_load_lds_dwordx4 v[222:223], off
	ds_read_b128 v[182:185], v149 offset:16384
	ds_read_b128 v[186:189], v149 offset:17408
	ds_read_b128 v[194:197], v149 offset:18432
	ds_read_b128 v[198:201], v149 offset:19456
	ds_read_b128 v[202:205], v149 offset:20480
	ds_read_b128 v[206:209], v149 offset:21504
	ds_read_b128 v[210:213], v149 offset:22528
	ds_read_b128 v[214:217], v149 offset:23552
	s_waitcnt vmcnt(8)
	s_waitcnt lgkmcnt(0)
	s_barrier
	s_setprio 1
	s_waitcnt lgkmcnt(0)
	v_mfma_f32_16x16x32_bf16 v[60:63], v[150:153], v[182:185], v[60:63]
	v_mfma_f32_16x16x32_bf16 v[56:59], v[158:161], v[182:185], v[56:59]
	v_mfma_f32_16x16x32_bf16 v[52:55], v[150:153], v[194:197], v[52:55]
	v_mfma_f32_16x16x32_bf16 v[48:51], v[158:161], v[194:197], v[48:51]
	v_mfma_f32_16x16x32_bf16 v[36:39], v[150:153], v[202:205], v[36:39]
	v_mfma_f32_16x16x32_bf16 v[32:35], v[158:161], v[202:205], v[32:35]
	v_mfma_f32_16x16x32_bf16 v[20:23], v[150:153], v[210:213], v[20:23]
	v_mfma_f32_16x16x32_bf16 v[16:19], v[158:161], v[210:213], v[16:19]
	v_mfma_f32_16x16x32_bf16 v[60:63], v[154:157], v[186:189], v[60:63]
	v_mfma_f32_16x16x32_bf16 v[56:59], v[162:165], v[186:189], v[56:59]
	v_mfma_f32_16x16x32_bf16 v[52:55], v[154:157], v[198:201], v[52:55]
	v_mfma_f32_16x16x32_bf16 v[48:51], v[162:165], v[198:201], v[48:51]
	v_mfma_f32_16x16x32_bf16 v[36:39], v[154:157], v[206:209], v[36:39]
	v_mfma_f32_16x16x32_bf16 v[32:35], v[162:165], v[206:209], v[32:35]
	v_mfma_f32_16x16x32_bf16 v[20:23], v[154:157], v[214:217], v[20:23]
	v_mfma_f32_16x16x32_bf16 v[16:19], v[162:165], v[214:217], v[16:19]
	s_setprio 0
	s_setprio 1
	v_mfma_f32_16x16x32_bf16 v[44:47], v[166:169], v[182:185], v[44:47]
	v_mfma_f32_16x16x32_bf16 v[40:43], v[174:177], v[182:185], v[40:43]
	v_mfma_f32_16x16x32_bf16 v[28:31], v[166:169], v[194:197], v[28:31]
	v_mfma_f32_16x16x32_bf16 v[24:27], v[174:177], v[194:197], v[24:27]
	v_mfma_f32_16x16x32_bf16 v[12:15], v[166:169], v[202:205], v[12:15]
	v_mfma_f32_16x16x32_bf16 v[8:11], v[174:177], v[202:205], v[8:11]
	v_mfma_f32_16x16x32_bf16 v[4:7], v[166:169], v[210:213], v[4:7]
	v_mfma_f32_16x16x32_bf16 v[0:3], v[174:177], v[210:213], v[0:3]
	v_mfma_f32_16x16x32_bf16 v[44:47], v[170:173], v[186:189], v[44:47]
	v_mfma_f32_16x16x32_bf16 v[40:43], v[178:181], v[186:189], v[40:43]
	v_mfma_f32_16x16x32_bf16 v[28:31], v[170:173], v[198:201], v[28:31]
	v_mfma_f32_16x16x32_bf16 v[24:27], v[178:181], v[198:201], v[24:27]
	v_mfma_f32_16x16x32_bf16 v[12:15], v[170:173], v[206:209], v[12:15]
	v_mfma_f32_16x16x32_bf16 v[8:11], v[178:181], v[206:209], v[8:11]
	v_mfma_f32_16x16x32_bf16 v[4:7], v[170:173], v[214:217], v[4:7]
	v_mfma_f32_16x16x32_bf16 v[0:3], v[178:181], v[214:217], v[0:3]
	s_setprio 0
	s_barrier
	s_add_i32 s68, 0, 0x18000
	s_add_i32 s69, 0, 0x1c000
	v_add_u32_e32 v162, s68, v145
	v_add_u32_e32 v178, s69, v145
	s_add_u32 s46, s46, 0x40000
	s_addc_u32 s47, s47, 0
	s_mov_b32 m0, s23
	v_lshl_add_u64 v[224:225], s[46:47], 0, v[134:135]
	global_load_lds_dwordx4 v[224:225], off
	v_lshl_add_u64 v[224:225], s[46:47], 0, v[130:131]
	s_mov_b32 m0, s33
	s_nop 0
	global_load_lds_dwordx4 v[224:225], off
	ds_read_b128 v[150:153], v162
	ds_read_b128 v[154:157], v162 offset:1024
	ds_read_b128 v[158:161], v162 offset:2048
	ds_read_b128 v[162:165], v162 offset:3072
	ds_read_b128 v[166:169], v178
	ds_read_b128 v[170:173], v178 offset:1024
	ds_read_b128 v[174:177], v178 offset:2048
	ds_read_b128 v[178:181], v178 offset:3072
	ds_read_b128 v[182:185], v149 offset:32768
	ds_read_b128 v[186:189], v149 offset:33792
	ds_read_b128 v[194:197], v149 offset:34816
	ds_read_b128 v[198:201], v149 offset:35840
	ds_read_b128 v[202:205], v149 offset:36864
	ds_read_b128 v[206:209], v149 offset:37888
	ds_read_b128 v[210:213], v149 offset:38912
	ds_read_b128 v[214:217], v149 offset:39936
	s_waitcnt vmcnt(8)
	s_waitcnt lgkmcnt(0)
	s_barrier
	s_setprio 1
	s_waitcnt lgkmcnt(0)
	v_mfma_f32_16x16x32_bf16 v[124:127], v[150:153], v[182:185], v[124:127]
	v_mfma_f32_16x16x32_bf16 v[120:123], v[158:161], v[182:185], v[120:123]
	v_mfma_f32_16x16x32_bf16 v[116:119], v[150:153], v[194:197], v[116:119]
	v_mfma_f32_16x16x32_bf16 v[112:115], v[158:161], v[194:197], v[112:115]
	v_mfma_f32_16x16x32_bf16 v[100:103], v[150:153], v[202:205], v[100:103]
	v_mfma_f32_16x16x32_bf16 v[96:99], v[158:161], v[202:205], v[96:99]
	v_mfma_f32_16x16x32_bf16 v[84:87], v[150:153], v[210:213], v[84:87]
	v_mfma_f32_16x16x32_bf16 v[80:83], v[158:161], v[210:213], v[80:83]
	v_mfma_f32_16x16x32_bf16 v[124:127], v[154:157], v[186:189], v[124:127]
	v_mfma_f32_16x16x32_bf16 v[120:123], v[162:165], v[186:189], v[120:123]
	v_mfma_f32_16x16x32_bf16 v[116:119], v[154:157], v[198:201], v[116:119]
	v_mfma_f32_16x16x32_bf16 v[112:115], v[162:165], v[198:201], v[112:115]
	v_mfma_f32_16x16x32_bf16 v[100:103], v[154:157], v[206:209], v[100:103]
	v_mfma_f32_16x16x32_bf16 v[96:99], v[162:165], v[206:209], v[96:99]
	v_mfma_f32_16x16x32_bf16 v[84:87], v[154:157], v[214:217], v[84:87]
	v_mfma_f32_16x16x32_bf16 v[80:83], v[162:165], v[214:217], v[80:83]
	s_setprio 0
	s_setprio 1
	v_mfma_f32_16x16x32_bf16 v[108:111], v[166:169], v[182:185], v[108:111]
	v_mfma_f32_16x16x32_bf16 v[104:107], v[174:177], v[182:185], v[104:107]
	v_mfma_f32_16x16x32_bf16 v[92:95], v[166:169], v[194:197], v[92:95]
	v_mfma_f32_16x16x32_bf16 v[88:91], v[174:177], v[194:197], v[88:91]
	v_mfma_f32_16x16x32_bf16 v[76:79], v[166:169], v[202:205], v[76:79]
	v_mfma_f32_16x16x32_bf16 v[72:75], v[174:177], v[202:205], v[72:75]
	v_mfma_f32_16x16x32_bf16 v[68:71], v[166:169], v[210:213], v[68:71]
	v_mfma_f32_16x16x32_bf16 v[64:67], v[174:177], v[210:213], v[64:67]
	v_mfma_f32_16x16x32_bf16 v[108:111], v[170:173], v[186:189], v[108:111]
	v_mfma_f32_16x16x32_bf16 v[104:107], v[178:181], v[186:189], v[104:107]
	v_mfma_f32_16x16x32_bf16 v[92:95], v[170:173], v[198:201], v[92:95]
	v_mfma_f32_16x16x32_bf16 v[88:91], v[178:181], v[198:201], v[88:91]
	v_mfma_f32_16x16x32_bf16 v[76:79], v[170:173], v[206:209], v[76:79]
	v_mfma_f32_16x16x32_bf16 v[72:75], v[178:181], v[206:209], v[72:75]
	v_mfma_f32_16x16x32_bf16 v[68:71], v[170:173], v[214:217], v[68:71]
	v_mfma_f32_16x16x32_bf16 v[64:67], v[178:181], v[214:217], v[64:67]
	s_setprio 0
	s_barrier
	s_add_i32 s46, s68, s14
	v_lshl_add_u64 v[190:191], v[190:191], 0, s[4:5]
	s_mov_b32 m0, s46
	global_load_lds_dwordx4 v[190:191], off
	s_add_i32 m0, s46, 0x2000
	s_add_u32 s42, s42, 0x40080
	v_lshl_add_u64 v[190:191], v[218:219], 0, s[4:5]
	s_addc_u32 s43, s43, 0
	s_add_i32 s46, s69, s14
	global_load_lds_dwordx4 v[190:191], off
	v_lshl_add_u64 v[190:191], s[42:43], 0, v[132:133]
	s_mov_b32 m0, s46
	s_nop 0
	global_load_lds_dwordx4 v[190:191], off
	v_lshl_add_u64 v[190:191], s[42:43], 0, v[128:129]
	s_add_i32 m0, s46, 0x2000
	s_nop 0
	global_load_lds_dwordx4 v[190:191], off
	v_lshl_add_u64 v[190:191], v[220:221], 0, s[4:5]
	s_mov_b32 m0, s49
	s_nop 0
	global_load_lds_dwordx4 v[190:191], off
	v_lshl_add_u64 v[190:191], v[222:223], 0, s[4:5]
	s_mov_b32 m0, s50
	s_nop 0
	global_load_lds_dwordx4 v[190:191], off
	ds_read_b128 v[182:185], v149 offset:49152
	ds_read_b128 v[186:189], v149 offset:50176
	ds_read_b128 v[194:197], v149 offset:51200
	ds_read_b128 v[198:201], v149 offset:52224
	ds_read_b128 v[202:205], v149 offset:53248
	ds_read_b128 v[206:209], v149 offset:54272
	ds_read_b128 v[210:213], v149 offset:55296
	ds_read_b128 v[214:217], v149 offset:56320
	s_waitcnt vmcnt(8)
	s_waitcnt lgkmcnt(0)
	s_barrier
	s_setprio 1
	s_waitcnt lgkmcnt(0)
	v_mfma_f32_16x16x32_bf16 v[60:63], v[150:153], v[182:185], v[60:63]
	v_mfma_f32_16x16x32_bf16 v[56:59], v[158:161], v[182:185], v[56:59]
	v_mfma_f32_16x16x32_bf16 v[52:55], v[150:153], v[194:197], v[52:55]
	v_mfma_f32_16x16x32_bf16 v[48:51], v[158:161], v[194:197], v[48:51]
	v_mfma_f32_16x16x32_bf16 v[36:39], v[150:153], v[202:205], v[36:39]
	v_mfma_f32_16x16x32_bf16 v[32:35], v[158:161], v[202:205], v[32:35]
	v_mfma_f32_16x16x32_bf16 v[20:23], v[150:153], v[210:213], v[20:23]
	v_mfma_f32_16x16x32_bf16 v[16:19], v[158:161], v[210:213], v[16:19]
	v_mfma_f32_16x16x32_bf16 v[60:63], v[154:157], v[186:189], v[60:63]
	v_mfma_f32_16x16x32_bf16 v[56:59], v[162:165], v[186:189], v[56:59]
	v_mfma_f32_16x16x32_bf16 v[52:55], v[154:157], v[198:201], v[52:55]
	v_mfma_f32_16x16x32_bf16 v[48:51], v[162:165], v[198:201], v[48:51]
	v_mfma_f32_16x16x32_bf16 v[36:39], v[154:157], v[206:209], v[36:39]
	v_mfma_f32_16x16x32_bf16 v[32:35], v[162:165], v[206:209], v[32:35]
	v_mfma_f32_16x16x32_bf16 v[20:23], v[154:157], v[214:217], v[20:23]
	v_mfma_f32_16x16x32_bf16 v[16:19], v[162:165], v[214:217], v[16:19]
	s_setprio 0
	s_setprio 1
	v_mfma_f32_16x16x32_bf16 v[44:47], v[166:169], v[182:185], v[44:47]
	v_mfma_f32_16x16x32_bf16 v[40:43], v[174:177], v[182:185], v[40:43]
	v_mfma_f32_16x16x32_bf16 v[28:31], v[166:169], v[194:197], v[28:31]
	v_mfma_f32_16x16x32_bf16 v[24:27], v[174:177], v[194:197], v[24:27]
	v_mfma_f32_16x16x32_bf16 v[12:15], v[166:169], v[202:205], v[12:15]
	v_mfma_f32_16x16x32_bf16 v[8:11], v[174:177], v[202:205], v[8:11]
	v_mfma_f32_16x16x32_bf16 v[4:7], v[166:169], v[210:213], v[4:7]
	v_mfma_f32_16x16x32_bf16 v[0:3], v[174:177], v[210:213], v[0:3]
	v_mfma_f32_16x16x32_bf16 v[44:47], v[170:173], v[186:189], v[44:47]
	v_mfma_f32_16x16x32_bf16 v[40:43], v[178:181], v[186:189], v[40:43]
	v_mfma_f32_16x16x32_bf16 v[28:31], v[170:173], v[198:201], v[28:31]
	v_mfma_f32_16x16x32_bf16 v[24:27], v[178:181], v[198:201], v[24:27]
	v_mfma_f32_16x16x32_bf16 v[12:15], v[170:173], v[206:209], v[12:15]
	v_mfma_f32_16x16x32_bf16 v[8:11], v[178:181], v[206:209], v[8:11]
	v_mfma_f32_16x16x32_bf16 v[4:7], v[170:173], v[214:217], v[4:7]
	v_mfma_f32_16x16x32_bf16 v[0:3], v[178:181], v[214:217], v[0:3]
	s_setprio 0
	s_barrier
	s_add_i32 s67, s67, 2
	s_add_u32 s36, s36, 0x100
	s_addc_u32 s37, s37, 0
	s_add_u32 s65, s65, 0x100
	s_addc_u32 s66, s66, 0
	s_cmp_gt_u32 s67, 13
	s_cbranch_scc0 .LBB0_677
	s_and_b64 vcc, exec, s[6:7]
	s_cbranch_vccz .LBB0_680
	s_barrier

.LBB0_885:
	s_add_u32 s34, s30, 0xfffc0080
	s_addc_u32 s35, s31, -1
	s_cmp_eq_u32 s53, 12
	s_cselect_b32 s37, s17, s35
	s_cselect_b32 s36, s27, s34
	s_cselect_b32 s35, s13, s52
	s_cselect_b32 s34, s50, s51
	v_lshl_add_u64 v[214:215], s[30:31], 0, v[132:133]
	s_add_i32 m0, s15, 0xc000
	s_nop 0
	global_load_lds_dwordx4 v[214:215], off
	v_lshl_add_u64 v[214:215], s[30:31], 0, v[134:135]
	s_add_i32 m0, s15, 0xe000
	s_nop 0
	global_load_lds_dwordx4 v[214:215], off
	ds_read_b128 v[140:143], v149
	ds_read_b128 v[152:155], v149 offset:1024
	ds_read_b128 v[156:159], v149 offset:2048
	ds_read_b128 v[160:163], v149 offset:3072
	ds_read_b128 v[164:167], v150
	ds_read_b128 v[168:171], v150 offset:1024
	ds_read_b128 v[172:175], v150 offset:2048
	ds_read_b128 v[176:179], v150 offset:3072
	ds_read_b128 v[180:183], v151
	ds_read_b128 v[184:187], v151 offset:1024
	ds_read_b128 v[188:191], v151 offset:2048
	ds_read_b128 v[194:197], v151 offset:3072
	ds_read_b128 v[198:201], v151 offset:4096
	ds_read_b128 v[202:205], v151 offset:5120
	ds_read_b128 v[206:209], v151 offset:6144
	ds_read_b128 v[210:213], v151 offset:7168
	s_waitcnt vmcnt(8)
	s_waitcnt lgkmcnt(0)
	s_barrier
	s_setprio 1
	s_waitcnt lgkmcnt(0)
	v_mfma_f32_16x16x32_bf16 v[124:127], v[140:143], v[180:183], v[124:127]
	v_mfma_f32_16x16x32_bf16 v[120:123], v[156:159], v[180:183], v[120:123]
	v_mfma_f32_16x16x32_bf16 v[108:111], v[140:143], v[188:191], v[108:111]
	v_mfma_f32_16x16x32_bf16 v[104:107], v[156:159], v[188:191], v[104:107]
	v_mfma_f32_16x16x32_bf16 v[92:95], v[140:143], v[198:201], v[92:95]
	v_mfma_f32_16x16x32_bf16 v[88:91], v[156:159], v[198:201], v[88:91]
	v_mfma_f32_16x16x32_bf16 v[76:79], v[140:143], v[206:209], v[76:79]
	v_mfma_f32_16x16x32_bf16 v[72:75], v[156:159], v[206:209], v[72:75]
	v_mfma_f32_16x16x32_bf16 v[124:127], v[152:155], v[184:187], v[124:127]
	v_mfma_f32_16x16x32_bf16 v[120:123], v[160:163], v[184:187], v[120:123]
	v_mfma_f32_16x16x32_bf16 v[108:111], v[152:155], v[194:197], v[108:111]
	v_mfma_f32_16x16x32_bf16 v[104:107], v[160:163], v[194:197], v[104:107]
	v_mfma_f32_16x16x32_bf16 v[92:95], v[152:155], v[202:205], v[92:95]
	v_mfma_f32_16x16x32_bf16 v[88:91], v[160:163], v[202:205], v[88:91]
	v_mfma_f32_16x16x32_bf16 v[76:79], v[152:155], v[210:213], v[76:79]
	v_mfma_f32_16x16x32_bf16 v[72:75], v[160:163], v[210:213], v[72:75]
	s_setprio 0
	s_setprio 1
	v_mfma_f32_16x16x32_bf16 v[116:119], v[164:167], v[180:183], v[116:119]
	v_mfma_f32_16x16x32_bf16 v[112:115], v[172:175], v[180:183], v[112:115]
	v_mfma_f32_16x16x32_bf16 v[100:103], v[164:167], v[188:191], v[100:103]
	v_mfma_f32_16x16x32_bf16 v[96:99], v[172:175], v[188:191], v[96:99]
	v_mfma_f32_16x16x32_bf16 v[84:87], v[164:167], v[198:201], v[84:87]
	v_mfma_f32_16x16x32_bf16 v[80:83], v[172:175], v[198:201], v[80:83]
	v_mfma_f32_16x16x32_bf16 v[68:71], v[164:167], v[206:209], v[68:71]
	v_mfma_f32_16x16x32_bf16 v[64:67], v[172:175], v[206:209], v[64:67]
	v_mfma_f32_16x16x32_bf16 v[116:119], v[168:171], v[184:187], v[116:119]
	v_mfma_f32_16x16x32_bf16 v[112:115], v[176:179], v[184:187], v[112:115]
	v_mfma_f32_16x16x32_bf16 v[100:103], v[168:171], v[194:197], v[100:103]
	v_mfma_f32_16x16x32_bf16 v[96:99], v[176:179], v[194:197], v[96:99]
	v_mfma_f32_16x16x32_bf16 v[84:87], v[168:171], v[202:205], v[84:87]
	v_mfma_f32_16x16x32_bf16 v[80:83], v[176:179], v[202:205], v[80:83]
	v_mfma_f32_16x16x32_bf16 v[68:71], v[168:171], v[210:213], v[68:71]
	v_mfma_f32_16x16x32_bf16 v[64:67], v[176:179], v[210:213], v[64:67]
	s_setprio 0
	s_barrier
	s_add_i32 s54, s47, s14
	v_lshl_add_u64 v[214:215], s[34:35], 0, v[128:129]
	s_mov_b32 m0, s54
	global_load_lds_dwordx4 v[214:215], off
	s_add_i32 m0, s54, 0x2000
	s_add_u32 s54, s34, 0x40000
	v_lshl_add_u64 v[216:217], s[34:35], 0, v[130:131]
	s_addc_u32 s55, s35, 0
	s_add_i32 s56, s48, s14
	global_load_lds_dwordx4 v[216:217], off
	v_lshl_add_u64 v[218:219], s[54:55], 0, v[128:129]
	s_mov_b32 m0, s56
	v_lshl_add_u64 v[220:221], s[36:37], 0, v[130:131]
	global_load_lds_dwordx4 v[218:219], off
	v_lshl_add_u64 v[218:219], s[54:55], 0, v[130:131]
	s_add_i32 m0, s56, 0x2000
	s_nop 0
	global_load_lds_dwordx4 v[218:219], off
	v_lshl_add_u64 v[218:219], s[36:37], 0, v[128:129]
	s_mov_b32 m0, s15
	s_nop 0
	global_load_lds_dwordx4 v[218:219], off
	s_mov_b32 m0, s20
	s_nop 0
	global_load_lds_dwordx4 v[220:221], off
	ds_read_b128 v[180:183], v151 offset:16384
	ds_read_b128 v[184:187], v151 offset:17408
	ds_read_b128 v[188:191], v151 offset:18432
	ds_read_b128 v[194:197], v151 offset:19456
	ds_read_b128 v[198:201], v151 offset:20480
	ds_read_b128 v[202:205], v151 offset:21504
	ds_read_b128 v[206:209], v151 offset:22528
	ds_read_b128 v[210:213], v151 offset:23552
	s_waitcnt vmcnt(8)
	s_waitcnt lgkmcnt(0)
	s_barrier
	s_setprio 1
	s_waitcnt lgkmcnt(0)
	v_mfma_f32_16x16x32_bf16 v[60:63], v[140:143], v[180:183], v[60:63]
	v_mfma_f32_16x16x32_bf16 v[56:59], v[156:159], v[180:183], v[56:59]
	v_mfma_f32_16x16x32_bf16 v[44:47], v[140:143], v[188:191], v[44:47]
	v_mfma_f32_16x16x32_bf16 v[40:43], v[156:159], v[188:191], v[40:43]
	v_mfma_f32_16x16x32_bf16 v[28:31], v[140:143], v[198:201], v[28:31]
	v_mfma_f32_16x16x32_bf16 v[24:27], v[156:159], v[198:201], v[24:27]
	v_mfma_f32_16x16x32_bf16 v[12:15], v[140:143], v[206:209], v[12:15]
	v_mfma_f32_16x16x32_bf16 v[8:11], v[156:159], v[206:209], v[8:11]
	v_mfma_f32_16x16x32_bf16 v[60:63], v[152:155], v[184:187], v[60:63]
	v_mfma_f32_16x16x32_bf16 v[56:59], v[160:163], v[184:187], v[56:59]
	v_mfma_f32_16x16x32_bf16 v[44:47], v[152:155], v[194:197], v[44:47]
	v_mfma_f32_16x16x32_bf16 v[40:43], v[160:163], v[194:197], v[40:43]
	v_mfma_f32_16x16x32_bf16 v[28:31], v[152:155], v[202:205], v[28:31]
	v_mfma_f32_16x16x32_bf16 v[24:27], v[160:163], v[202:205], v[24:27]
	v_mfma_f32_16x16x32_bf16 v[12:15], v[152:155], v[210:213], v[12:15]
	v_mfma_f32_16x16x32_bf16 v[8:11], v[160:163], v[210:213], v[8:11]
	s_setprio 0
	s_setprio 1
	v_mfma_f32_16x16x32_bf16 v[52:55], v[164:167], v[180:183], v[52:55]
	v_mfma_f32_16x16x32_bf16 v[48:51], v[172:175], v[180:183], v[48:51]
	v_mfma_f32_16x16x32_bf16 v[36:39], v[164:167], v[188:191], v[36:39]
	v_mfma_f32_16x16x32_bf16 v[32:35], v[172:175], v[188:191], v[32:35]
	v_mfma_f32_16x16x32_bf16 v[20:23], v[164:167], v[198:201], v[20:23]
	v_mfma_f32_16x16x32_bf16 v[16:19], v[172:175], v[198:201], v[16:19]
	v_mfma_f32_16x16x32_bf16 v[4:7], v[164:167], v[206:209], v[4:7]
	v_mfma_f32_16x16x32_bf16 v[0:3], v[172:175], v[206:209], v[0:3]
	v_mfma_f32_16x16x32_bf16 v[52:55], v[168:171], v[184:187], v[52:55]
	v_mfma_f32_16x16x32_bf16 v[48:51], v[176:179], v[184:187], v[48:51]
	v_mfma_f32_16x16x32_bf16 v[36:39], v[168:171], v[194:197], v[36:39]
	v_mfma_f32_16x16x32_bf16 v[32:35], v[176:179], v[194:197], v[32:35]
	v_mfma_f32_16x16x32_bf16 v[20:23], v[168:171], v[202:205], v[20:23]
	v_mfma_f32_16x16x32_bf16 v[16:19], v[176:179], v[202:205], v[16:19]
	v_mfma_f32_16x16x32_bf16 v[4:7], v[168:171], v[210:213], v[4:7]
	v_mfma_f32_16x16x32_bf16 v[0:3], v[176:179], v[210:213], v[0:3]
	s_setprio 0
	s_barrier
	s_add_i32 s54, 0, 0x18000
	s_add_i32 s55, 0, 0x1c000
	v_add_u32_e32 v160, s54, v145
	v_add_u32_e32 v176, s55, v145
	s_add_u32 s36, s36, 0x40000
	s_addc_u32 s37, s37, 0
	s_mov_b32 m0, s21
	v_lshl_add_u64 v[222:223], s[36:37], 0, v[128:129]
	global_load_lds_dwordx4 v[222:223], off
	v_lshl_add_u64 v[222:223], s[36:37], 0, v[130:131]
	s_mov_b32 m0, s33
	s_nop 0
	global_load_lds_dwordx4 v[222:223], off
	ds_read_b128 v[140:143], v160
	ds_read_b128 v[152:155], v160 offset:1024
	ds_read_b128 v[156:159], v160 offset:2048
	ds_read_b128 v[160:163], v160 offset:3072
	ds_read_b128 v[164:167], v176
	ds_read_b128 v[168:171], v176 offset:1024
	ds_read_b128 v[172:175], v176 offset:2048
	ds_read_b128 v[176:179], v176 offset:3072
	ds_read_b128 v[180:183], v151 offset:32768
	ds_read_b128 v[184:187], v151 offset:33792
	ds_read_b128 v[188:191], v151 offset:34816
	ds_read_b128 v[194:197], v151 offset:35840
	ds_read_b128 v[198:201], v151 offset:36864
	ds_read_b128 v[202:205], v151 offset:37888
	ds_read_b128 v[206:209], v151 offset:38912
	ds_read_b128 v[210:213], v151 offset:39936
	s_waitcnt vmcnt(8)
	s_waitcnt lgkmcnt(0)
	s_barrier
	s_setprio 1
	s_waitcnt lgkmcnt(0)
	v_mfma_f32_16x16x32_bf16 v[124:127], v[140:143], v[180:183], v[124:127]
	v_mfma_f32_16x16x32_bf16 v[120:123], v[156:159], v[180:183], v[120:123]
	v_mfma_f32_16x16x32_bf16 v[108:111], v[140:143], v[188:191], v[108:111]
	v_mfma_f32_16x16x32_bf16 v[104:107], v[156:159], v[188:191], v[104:107]
	v_mfma_f32_16x16x32_bf16 v[92:95], v[140:143], v[198:201], v[92:95]
	v_mfma_f32_16x16x32_bf16 v[88:91], v[156:159], v[198:201], v[88:91]
	v_mfma_f32_16x16x32_bf16 v[76:79], v[140:143], v[206:209], v[76:79]
	v_mfma_f32_16x16x32_bf16 v[72:75], v[156:159], v[206:209], v[72:75]
	v_mfma_f32_16x16x32_bf16 v[124:127], v[152:155], v[184:187], v[124:127]
	v_mfma_f32_16x16x32_bf16 v[120:123], v[160:163], v[184:187], v[120:123]
	v_mfma_f32_16x16x32_bf16 v[108:111], v[152:155], v[194:197], v[108:111]
	v_mfma_f32_16x16x32_bf16 v[104:107], v[160:163], v[194:197], v[104:107]
	v_mfma_f32_16x16x32_bf16 v[92:95], v[152:155], v[202:205], v[92:95]
	v_mfma_f32_16x16x32_bf16 v[88:91], v[160:163], v[202:205], v[88:91]
	v_mfma_f32_16x16x32_bf16 v[76:79], v[152:155], v[210:213], v[76:79]
	v_mfma_f32_16x16x32_bf16 v[72:75], v[160:163], v[210:213], v[72:75]
	s_setprio 0
	s_setprio 1
	v_mfma_f32_16x16x32_bf16 v[116:119], v[164:167], v[180:183], v[116:119]
	v_mfma_f32_16x16x32_bf16 v[112:115], v[172:175], v[180:183], v[112:115]
	v_mfma_f32_16x16x32_bf16 v[100:103], v[164:167], v[188:191], v[100:103]
	v_mfma_f32_16x16x32_bf16 v[96:99], v[172:175], v[188:191], v[96:99]
	v_mfma_f32_16x16x32_bf16 v[84:87], v[164:167], v[198:201], v[84:87]
	v_mfma_f32_16x16x32_bf16 v[80:83], v[172:175], v[198:201], v[80:83]
	v_mfma_f32_16x16x32_bf16 v[68:71], v[164:167], v[206:209], v[68:71]
	v_mfma_f32_16x16x32_bf16 v[64:67], v[172:175], v[206:209], v[64:67]
	v_mfma_f32_16x16x32_bf16 v[116:119], v[168:171], v[184:187], v[116:119]
	v_mfma_f32_16x16x32_bf16 v[112:115], v[176:179], v[184:187], v[112:115]
	v_mfma_f32_16x16x32_bf16 v[100:103], v[168:171], v[194:197], v[100:103]
	v_mfma_f32_16x16x32_bf16 v[96:99], v[176:179], v[194:197], v[96:99]
	v_mfma_f32_16x16x32_bf16 v[84:87], v[168:171], v[202:205], v[84:87]
	v_mfma_f32_16x16x32_bf16 v[80:83], v[176:179], v[202:205], v[80:83]
	v_mfma_f32_16x16x32_bf16 v[68:71], v[168:171], v[210:213], v[68:71]
	v_mfma_f32_16x16x32_bf16 v[64:67], v[176:179], v[210:213], v[64:67]
	s_setprio 0
	s_barrier
	s_add_i32 s36, s54, s14
	v_lshl_add_u64 v[214:215], v[214:215], 0, s[8:9]
	s_mov_b32 m0, s36
	global_load_lds_dwordx4 v[214:215], off
	s_add_i32 m0, s36, 0x2000
	s_add_u32 s34, s34, 0x40080
	v_lshl_add_u64 v[214:215], v[216:217], 0, s[8:9]
	s_addc_u32 s35, s35, 0
	s_add_i32 s36, s55, s14
	global_load_lds_dwordx4 v[214:215], off
	v_lshl_add_u64 v[214:215], s[34:35], 0, v[128:129]
	s_mov_b32 m0, s36
	s_nop 0
	global_load_lds_dwordx4 v[214:215], off
	v_lshl_add_u64 v[214:215], s[34:35], 0, v[130:131]
	s_add_i32 m0, s36, 0x2000
	s_nop 0
	global_load_lds_dwordx4 v[214:215], off
	v_lshl_add_u64 v[214:215], v[218:219], 0, s[8:9]
	s_mov_b32 m0, s45
	s_nop 0
	global_load_lds_dwordx4 v[214:215], off
	v_lshl_add_u64 v[214:215], v[220:221], 0, s[8:9]
	s_mov_b32 m0, s46
	s_nop 0
	global_load_lds_dwordx4 v[214:215], off
	ds_read_b128 v[180:183], v151 offset:49152
	ds_read_b128 v[184:187], v151 offset:50176
	ds_read_b128 v[188:191], v151 offset:51200
	ds_read_b128 v[194:197], v151 offset:52224
	ds_read_b128 v[198:201], v151 offset:53248
	ds_read_b128 v[202:205], v151 offset:54272
	ds_read_b128 v[206:209], v151 offset:55296
	ds_read_b128 v[210:213], v151 offset:56320
	s_waitcnt vmcnt(8)
	s_waitcnt lgkmcnt(0)
	s_barrier
	s_setprio 1
	s_waitcnt lgkmcnt(0)
	v_mfma_f32_16x16x32_bf16 v[60:63], v[140:143], v[180:183], v[60:63]
	v_mfma_f32_16x16x32_bf16 v[56:59], v[156:159], v[180:183], v[56:59]
	v_mfma_f32_16x16x32_bf16 v[44:47], v[140:143], v[188:191], v[44:47]
	v_mfma_f32_16x16x32_bf16 v[40:43], v[156:159], v[188:191], v[40:43]
	v_mfma_f32_16x16x32_bf16 v[28:31], v[140:143], v[198:201], v[28:31]
	v_mfma_f32_16x16x32_bf16 v[24:27], v[156:159], v[198:201], v[24:27]
	v_mfma_f32_16x16x32_bf16 v[12:15], v[140:143], v[206:209], v[12:15]
	v_mfma_f32_16x16x32_bf16 v[8:11], v[156:159], v[206:209], v[8:11]
	v_mfma_f32_16x16x32_bf16 v[60:63], v[152:155], v[184:187], v[60:63]
	v_mfma_f32_16x16x32_bf16 v[56:59], v[160:163], v[184:187], v[56:59]
	v_mfma_f32_16x16x32_bf16 v[44:47], v[152:155], v[194:197], v[44:47]
	v_mfma_f32_16x16x32_bf16 v[40:43], v[160:163], v[194:197], v[40:43]
	v_mfma_f32_16x16x32_bf16 v[28:31], v[152:155], v[202:205], v[28:31]
	v_mfma_f32_16x16x32_bf16 v[24:27], v[160:163], v[202:205], v[24:27]
	v_mfma_f32_16x16x32_bf16 v[12:15], v[152:155], v[210:213], v[12:15]
	v_mfma_f32_16x16x32_bf16 v[8:11], v[160:163], v[210:213], v[8:11]
	s_setprio 0
	s_setprio 1
	v_mfma_f32_16x16x32_bf16 v[52:55], v[164:167], v[180:183], v[52:55]
	v_mfma_f32_16x16x32_bf16 v[48:51], v[172:175], v[180:183], v[48:51]
	v_mfma_f32_16x16x32_bf16 v[36:39], v[164:167], v[188:191], v[36:39]
	v_mfma_f32_16x16x32_bf16 v[32:35], v[172:175], v[188:191], v[32:35]
	v_mfma_f32_16x16x32_bf16 v[20:23], v[164:167], v[198:201], v[20:23]
	v_mfma_f32_16x16x32_bf16 v[16:19], v[172:175], v[198:201], v[16:19]
	v_mfma_f32_16x16x32_bf16 v[4:7], v[164:167], v[206:209], v[4:7]
	v_mfma_f32_16x16x32_bf16 v[0:3], v[172:175], v[206:209], v[0:3]
	v_mfma_f32_16x16x32_bf16 v[52:55], v[168:171], v[184:187], v[52:55]
	v_mfma_f32_16x16x32_bf16 v[48:51], v[176:179], v[184:187], v[48:51]
	v_mfma_f32_16x16x32_bf16 v[36:39], v[168:171], v[194:197], v[36:39]
	v_mfma_f32_16x16x32_bf16 v[32:35], v[176:179], v[194:197], v[32:35]
	v_mfma_f32_16x16x32_bf16 v[20:23], v[168:171], v[202:205], v[20:23]
	v_mfma_f32_16x16x32_bf16 v[16:19], v[176:179], v[202:205], v[16:19]
	v_mfma_f32_16x16x32_bf16 v[4:7], v[168:171], v[210:213], v[4:7]
	v_mfma_f32_16x16x32_bf16 v[0:3], v[176:179], v[210:213], v[0:3]
	s_setprio 0
	s_barrier
	s_add_i32 s53, s53, 2
	s_add_u32 s30, s30, 0x100
	s_addc_u32 s31, s31, 0
	s_add_u32 s51, s51, 0x100
	s_addc_u32 s52, s52, 0
	s_cmp_gt_u32 s53, 13
	s_cbranch_scc0 .LBB0_885
	s_and_b64 vcc, exec, s[10:11]
	s_cbranch_vccz .LBB0_888
	s_barrier

.LBB0_974:
	s_add_u32 s28, s26, 0xfffc0080
	s_addc_u32 s29, s27, -1
	s_cmp_eq_u32 s51, 12
	s_cselect_b32 s31, s17, s29
	s_cselect_b32 s30, s47, s28
	s_cselect_b32 s29, s13, s50
	s_cselect_b32 s28, s48, s49
	v_lshl_add_u64 v[146:147], s[26:27], 0, v[138:139]
	s_add_i32 m0, s33, 0xc000
	s_nop 0
	global_load_lds_dwordx4 v[146:147], off
	v_lshl_add_u64 v[146:147], s[26:27], 0, v[140:141]
	s_add_i32 m0, s33, 0xe000
	s_nop 0
	global_load_lds_dwordx4 v[146:147], off
	ds_read_b128 v[154:157], v150
	ds_read_b128 v[158:161], v150 offset:1024
	ds_read_b128 v[162:165], v150 offset:2048
	ds_read_b128 v[166:169], v150 offset:3072
	ds_read_b128 v[170:173], v151
	ds_read_b128 v[174:177], v151 offset:1024
	ds_read_b128 v[178:181], v151 offset:2048
	ds_read_b128 v[182:185], v151 offset:3072
	ds_read_b128 v[186:189], v152
	ds_read_b128 v[194:197], v152 offset:1024
	ds_read_b128 v[198:201], v152 offset:2048
	ds_read_b128 v[202:205], v152 offset:3072
	ds_read_b128 v[206:209], v152 offset:4096
	ds_read_b128 v[210:213], v152 offset:5120
	ds_read_b128 v[214:217], v152 offset:6144
	ds_read_b128 v[218:221], v152 offset:7168
	s_waitcnt vmcnt(8)
	s_waitcnt lgkmcnt(0)
	s_barrier
	s_setprio 1
	s_waitcnt lgkmcnt(0)
	v_mfma_f32_16x16x32_bf16 v[124:127], v[154:157], v[186:189], v[124:127]
	v_mfma_f32_16x16x32_bf16 v[120:123], v[162:165], v[186:189], v[120:123]
	v_mfma_f32_16x16x32_bf16 v[108:111], v[154:157], v[198:201], v[108:111]
	v_mfma_f32_16x16x32_bf16 v[104:107], v[162:165], v[198:201], v[104:107]
	v_mfma_f32_16x16x32_bf16 v[92:95], v[154:157], v[206:209], v[92:95]
	v_mfma_f32_16x16x32_bf16 v[88:91], v[162:165], v[206:209], v[88:91]
	v_mfma_f32_16x16x32_bf16 v[76:79], v[154:157], v[214:217], v[76:79]
	v_mfma_f32_16x16x32_bf16 v[72:75], v[162:165], v[214:217], v[72:75]
	v_mfma_f32_16x16x32_bf16 v[124:127], v[158:161], v[194:197], v[124:127]
	v_mfma_f32_16x16x32_bf16 v[120:123], v[166:169], v[194:197], v[120:123]
	v_mfma_f32_16x16x32_bf16 v[108:111], v[158:161], v[202:205], v[108:111]
	v_mfma_f32_16x16x32_bf16 v[104:107], v[166:169], v[202:205], v[104:107]
	v_mfma_f32_16x16x32_bf16 v[92:95], v[158:161], v[210:213], v[92:95]
	v_mfma_f32_16x16x32_bf16 v[88:91], v[166:169], v[210:213], v[88:91]
	v_mfma_f32_16x16x32_bf16 v[76:79], v[158:161], v[218:221], v[76:79]
	v_mfma_f32_16x16x32_bf16 v[72:75], v[166:169], v[218:221], v[72:75]
	s_setprio 0
	s_setprio 1
	v_mfma_f32_16x16x32_bf16 v[116:119], v[170:173], v[186:189], v[116:119]
	v_mfma_f32_16x16x32_bf16 v[112:115], v[178:181], v[186:189], v[112:115]
	v_mfma_f32_16x16x32_bf16 v[100:103], v[170:173], v[198:201], v[100:103]
	v_mfma_f32_16x16x32_bf16 v[96:99], v[178:181], v[198:201], v[96:99]
	v_mfma_f32_16x16x32_bf16 v[84:87], v[170:173], v[206:209], v[84:87]
	v_mfma_f32_16x16x32_bf16 v[80:83], v[178:181], v[206:209], v[80:83]
	v_mfma_f32_16x16x32_bf16 v[68:71], v[170:173], v[214:217], v[68:71]
	v_mfma_f32_16x16x32_bf16 v[64:67], v[178:181], v[214:217], v[64:67]
	v_mfma_f32_16x16x32_bf16 v[116:119], v[174:177], v[194:197], v[116:119]
	v_mfma_f32_16x16x32_bf16 v[112:115], v[182:185], v[194:197], v[112:115]
	v_mfma_f32_16x16x32_bf16 v[100:103], v[174:177], v[202:205], v[100:103]
	v_mfma_f32_16x16x32_bf16 v[96:99], v[182:185], v[202:205], v[96:99]
	v_mfma_f32_16x16x32_bf16 v[84:87], v[174:177], v[210:213], v[84:87]
	v_mfma_f32_16x16x32_bf16 v[80:83], v[182:185], v[210:213], v[80:83]
	v_mfma_f32_16x16x32_bf16 v[68:71], v[174:177], v[218:221], v[68:71]
	v_mfma_f32_16x16x32_bf16 v[64:67], v[182:185], v[218:221], v[64:67]
	s_setprio 0
	s_barrier
	s_add_i32 s52, s43, s14
	v_lshl_add_u64 v[146:147], s[28:29], 0, v[132:133]
	s_mov_b32 m0, s52
	global_load_lds_dwordx4 v[146:147], off
	s_add_i32 m0, s52, 0x2000
	s_add_u32 s52, s28, 0x40000
	v_lshl_add_u64 v[190:191], s[28:29], 0, v[128:129]
	s_addc_u32 s53, s29, 0
	s_add_i32 s54, s44, s14
	global_load_lds_dwordx4 v[190:191], off
	v_lshl_add_u64 v[222:223], s[52:53], 0, v[132:133]
	s_mov_b32 m0, s54
	v_lshl_add_u64 v[224:225], s[30:31], 0, v[130:131]
	global_load_lds_dwordx4 v[222:223], off
	v_lshl_add_u64 v[222:223], s[52:53], 0, v[128:129]
	s_add_i32 m0, s54, 0x2000
	s_nop 0
	global_load_lds_dwordx4 v[222:223], off
	v_lshl_add_u64 v[222:223], s[30:31], 0, v[134:135]
	s_mov_b32 m0, s33
	s_nop 0
	global_load_lds_dwordx4 v[222:223], off
	s_mov_b32 m0, s34
	s_nop 0
	global_load_lds_dwordx4 v[224:225], off
	ds_read_b128 v[186:189], v152 offset:16384
	ds_read_b128 v[194:197], v152 offset:17408
	ds_read_b128 v[198:201], v152 offset:18432
	ds_read_b128 v[202:205], v152 offset:19456
	ds_read_b128 v[206:209], v152 offset:20480
	ds_read_b128 v[210:213], v152 offset:21504
	ds_read_b128 v[214:217], v152 offset:22528
	ds_read_b128 v[218:221], v152 offset:23552
	s_waitcnt vmcnt(8)
	s_waitcnt lgkmcnt(0)
	s_barrier
	s_setprio 1
	s_waitcnt lgkmcnt(0)
	v_mfma_f32_16x16x32_bf16 v[60:63], v[154:157], v[186:189], v[60:63]
	v_mfma_f32_16x16x32_bf16 v[56:59], v[162:165], v[186:189], v[56:59]
	v_mfma_f32_16x16x32_bf16 v[44:47], v[154:157], v[198:201], v[44:47]
	v_mfma_f32_16x16x32_bf16 v[40:43], v[162:165], v[198:201], v[40:43]
	v_mfma_f32_16x16x32_bf16 v[28:31], v[154:157], v[206:209], v[28:31]
	v_mfma_f32_16x16x32_bf16 v[24:27], v[162:165], v[206:209], v[24:27]
	v_mfma_f32_16x16x32_bf16 v[12:15], v[154:157], v[214:217], v[12:15]
	v_mfma_f32_16x16x32_bf16 v[8:11], v[162:165], v[214:217], v[8:11]
	v_mfma_f32_16x16x32_bf16 v[60:63], v[158:161], v[194:197], v[60:63]
	v_mfma_f32_16x16x32_bf16 v[56:59], v[166:169], v[194:197], v[56:59]
	v_mfma_f32_16x16x32_bf16 v[44:47], v[158:161], v[202:205], v[44:47]
	v_mfma_f32_16x16x32_bf16 v[40:43], v[166:169], v[202:205], v[40:43]
	v_mfma_f32_16x16x32_bf16 v[28:31], v[158:161], v[210:213], v[28:31]
	v_mfma_f32_16x16x32_bf16 v[24:27], v[166:169], v[210:213], v[24:27]
	v_mfma_f32_16x16x32_bf16 v[12:15], v[158:161], v[218:221], v[12:15]
	v_mfma_f32_16x16x32_bf16 v[8:11], v[166:169], v[218:221], v[8:11]
	s_setprio 0
	s_setprio 1
	v_mfma_f32_16x16x32_bf16 v[52:55], v[170:173], v[186:189], v[52:55]
	v_mfma_f32_16x16x32_bf16 v[48:51], v[178:181], v[186:189], v[48:51]
	v_mfma_f32_16x16x32_bf16 v[36:39], v[170:173], v[198:201], v[36:39]
	v_mfma_f32_16x16x32_bf16 v[32:35], v[178:181], v[198:201], v[32:35]
	v_mfma_f32_16x16x32_bf16 v[20:23], v[170:173], v[206:209], v[20:23]
	v_mfma_f32_16x16x32_bf16 v[16:19], v[178:181], v[206:209], v[16:19]
	v_mfma_f32_16x16x32_bf16 v[4:7], v[170:173], v[214:217], v[4:7]
	v_mfma_f32_16x16x32_bf16 v[0:3], v[178:181], v[214:217], v[0:3]
	v_mfma_f32_16x16x32_bf16 v[52:55], v[174:177], v[194:197], v[52:55]
	v_mfma_f32_16x16x32_bf16 v[48:51], v[182:185], v[194:197], v[48:51]
	v_mfma_f32_16x16x32_bf16 v[36:39], v[174:177], v[202:205], v[36:39]
	v_mfma_f32_16x16x32_bf16 v[32:35], v[182:185], v[202:205], v[32:35]
	v_mfma_f32_16x16x32_bf16 v[20:23], v[174:177], v[210:213], v[20:23]
	v_mfma_f32_16x16x32_bf16 v[16:19], v[182:185], v[210:213], v[16:19]
	v_mfma_f32_16x16x32_bf16 v[4:7], v[174:177], v[218:221], v[4:7]
	v_mfma_f32_16x16x32_bf16 v[0:3], v[182:185], v[218:221], v[0:3]
	s_setprio 0
	s_barrier
	s_add_i32 s52, 0, 0x18000
	s_add_i32 s53, 0, 0x1c000
	v_add_u32_e32 v166, s52, v149
	v_add_u32_e32 v182, s53, v149
	s_add_u32 s30, s30, 0x40000
	s_addc_u32 s31, s31, 0
	s_mov_b32 m0, s35
	v_lshl_add_u64 v[226:227], s[30:31], 0, v[134:135]
	global_load_lds_dwordx4 v[226:227], off
	v_lshl_add_u64 v[226:227], s[30:31], 0, v[130:131]
	s_mov_b32 m0, s36
	s_nop 0
	global_load_lds_dwordx4 v[226:227], off
	ds_read_b128 v[154:157], v166
	ds_read_b128 v[158:161], v166 offset:1024
	ds_read_b128 v[162:165], v166 offset:2048
	ds_read_b128 v[166:169], v166 offset:3072
	ds_read_b128 v[170:173], v182
	ds_read_b128 v[174:177], v182 offset:1024
	ds_read_b128 v[178:181], v182 offset:2048
	ds_read_b128 v[182:185], v182 offset:3072
	ds_read_b128 v[186:189], v152 offset:32768
	ds_read_b128 v[194:197], v152 offset:33792
	ds_read_b128 v[198:201], v152 offset:34816
	ds_read_b128 v[202:205], v152 offset:35840
	ds_read_b128 v[206:209], v152 offset:36864
	ds_read_b128 v[210:213], v152 offset:37888
	ds_read_b128 v[214:217], v152 offset:38912
	ds_read_b128 v[218:221], v152 offset:39936
	s_waitcnt vmcnt(8)
	s_waitcnt lgkmcnt(0)
	s_barrier
	s_setprio 1
	s_waitcnt lgkmcnt(0)
	v_mfma_f32_16x16x32_bf16 v[124:127], v[154:157], v[186:189], v[124:127]
	v_mfma_f32_16x16x32_bf16 v[120:123], v[162:165], v[186:189], v[120:123]
	v_mfma_f32_16x16x32_bf16 v[108:111], v[154:157], v[198:201], v[108:111]
	v_mfma_f32_16x16x32_bf16 v[104:107], v[162:165], v[198:201], v[104:107]
	v_mfma_f32_16x16x32_bf16 v[92:95], v[154:157], v[206:209], v[92:95]
	v_mfma_f32_16x16x32_bf16 v[88:91], v[162:165], v[206:209], v[88:91]
	v_mfma_f32_16x16x32_bf16 v[76:79], v[154:157], v[214:217], v[76:79]
	v_mfma_f32_16x16x32_bf16 v[72:75], v[162:165], v[214:217], v[72:75]
	v_mfma_f32_16x16x32_bf16 v[124:127], v[158:161], v[194:197], v[124:127]
	v_mfma_f32_16x16x32_bf16 v[120:123], v[166:169], v[194:197], v[120:123]
	v_mfma_f32_16x16x32_bf16 v[108:111], v[158:161], v[202:205], v[108:111]
	v_mfma_f32_16x16x32_bf16 v[104:107], v[166:169], v[202:205], v[104:107]
	v_mfma_f32_16x16x32_bf16 v[92:95], v[158:161], v[210:213], v[92:95]
	v_mfma_f32_16x16x32_bf16 v[88:91], v[166:169], v[210:213], v[88:91]
	v_mfma_f32_16x16x32_bf16 v[76:79], v[158:161], v[218:221], v[76:79]
	v_mfma_f32_16x16x32_bf16 v[72:75], v[166:169], v[218:221], v[72:75]
	s_setprio 0
	s_setprio 1
	v_mfma_f32_16x16x32_bf16 v[116:119], v[170:173], v[186:189], v[116:119]
	v_mfma_f32_16x16x32_bf16 v[112:115], v[178:181], v[186:189], v[112:115]
	v_mfma_f32_16x16x32_bf16 v[100:103], v[170:173], v[198:201], v[100:103]
	v_mfma_f32_16x16x32_bf16 v[96:99], v[178:181], v[198:201], v[96:99]
	v_mfma_f32_16x16x32_bf16 v[84:87], v[170:173], v[206:209], v[84:87]
	v_mfma_f32_16x16x32_bf16 v[80:83], v[178:181], v[206:209], v[80:83]
	v_mfma_f32_16x16x32_bf16 v[68:71], v[170:173], v[214:217], v[68:71]
	v_mfma_f32_16x16x32_bf16 v[64:67], v[178:181], v[214:217], v[64:67]
	v_mfma_f32_16x16x32_bf16 v[116:119], v[174:177], v[194:197], v[116:119]
	v_mfma_f32_16x16x32_bf16 v[112:115], v[182:185], v[194:197], v[112:115]
	v_mfma_f32_16x16x32_bf16 v[100:103], v[174:177], v[202:205], v[100:103]
	v_mfma_f32_16x16x32_bf16 v[96:99], v[182:185], v[202:205], v[96:99]
	v_mfma_f32_16x16x32_bf16 v[84:87], v[174:177], v[210:213], v[84:87]
	v_mfma_f32_16x16x32_bf16 v[80:83], v[182:185], v[210:213], v[80:83]
	v_mfma_f32_16x16x32_bf16 v[68:71], v[174:177], v[218:221], v[68:71]
	v_mfma_f32_16x16x32_bf16 v[64:67], v[182:185], v[218:221], v[64:67]
	s_setprio 0
	s_barrier
	s_add_i32 s30, s52, s14
	v_lshl_add_u64 v[146:147], v[146:147], 0, s[6:7]
	s_mov_b32 m0, s30
	global_load_lds_dwordx4 v[146:147], off
	s_add_i32 m0, s30, 0x2000
	s_add_u32 s28, s28, 0x40080
	v_lshl_add_u64 v[146:147], v[190:191], 0, s[6:7]
	s_addc_u32 s29, s29, 0
	s_add_i32 s30, s53, s14
	global_load_lds_dwordx4 v[146:147], off
	v_lshl_add_u64 v[146:147], s[28:29], 0, v[132:133]
	s_mov_b32 m0, s30
	s_nop 0
	global_load_lds_dwordx4 v[146:147], off
	v_lshl_add_u64 v[146:147], s[28:29], 0, v[128:129]
	s_add_i32 m0, s30, 0x2000
	s_nop 0
	global_load_lds_dwordx4 v[146:147], off
	v_lshl_add_u64 v[146:147], v[222:223], 0, s[6:7]
	s_mov_b32 m0, s37
	s_nop 0
	global_load_lds_dwordx4 v[146:147], off
	v_lshl_add_u64 v[146:147], v[224:225], 0, s[6:7]
	s_mov_b32 m0, s42
	s_nop 0
	global_load_lds_dwordx4 v[146:147], off
	ds_read_b128 v[186:189], v152 offset:49152
	ds_read_b128 v[194:197], v152 offset:50176
	ds_read_b128 v[198:201], v152 offset:51200
	ds_read_b128 v[202:205], v152 offset:52224
	ds_read_b128 v[206:209], v152 offset:53248
	ds_read_b128 v[210:213], v152 offset:54272
	ds_read_b128 v[214:217], v152 offset:55296
	ds_read_b128 v[218:221], v152 offset:56320
	s_waitcnt vmcnt(8)
	s_waitcnt lgkmcnt(0)
	s_barrier
	s_setprio 1
	s_waitcnt lgkmcnt(0)
	v_mfma_f32_16x16x32_bf16 v[60:63], v[154:157], v[186:189], v[60:63]
	v_mfma_f32_16x16x32_bf16 v[56:59], v[162:165], v[186:189], v[56:59]
	v_mfma_f32_16x16x32_bf16 v[44:47], v[154:157], v[198:201], v[44:47]
	v_mfma_f32_16x16x32_bf16 v[40:43], v[162:165], v[198:201], v[40:43]
	v_mfma_f32_16x16x32_bf16 v[28:31], v[154:157], v[206:209], v[28:31]
	v_mfma_f32_16x16x32_bf16 v[24:27], v[162:165], v[206:209], v[24:27]
	v_mfma_f32_16x16x32_bf16 v[12:15], v[154:157], v[214:217], v[12:15]
	v_mfma_f32_16x16x32_bf16 v[8:11], v[162:165], v[214:217], v[8:11]
	v_mfma_f32_16x16x32_bf16 v[60:63], v[158:161], v[194:197], v[60:63]
	v_mfma_f32_16x16x32_bf16 v[56:59], v[166:169], v[194:197], v[56:59]
	v_mfma_f32_16x16x32_bf16 v[44:47], v[158:161], v[202:205], v[44:47]
	v_mfma_f32_16x16x32_bf16 v[40:43], v[166:169], v[202:205], v[40:43]
	v_mfma_f32_16x16x32_bf16 v[28:31], v[158:161], v[210:213], v[28:31]
	v_mfma_f32_16x16x32_bf16 v[24:27], v[166:169], v[210:213], v[24:27]
	v_mfma_f32_16x16x32_bf16 v[12:15], v[158:161], v[218:221], v[12:15]
	v_mfma_f32_16x16x32_bf16 v[8:11], v[166:169], v[218:221], v[8:11]
	s_setprio 0
	s_setprio 1
	v_mfma_f32_16x16x32_bf16 v[52:55], v[170:173], v[186:189], v[52:55]
	v_mfma_f32_16x16x32_bf16 v[48:51], v[178:181], v[186:189], v[48:51]
	v_mfma_f32_16x16x32_bf16 v[36:39], v[170:173], v[198:201], v[36:39]
	v_mfma_f32_16x16x32_bf16 v[32:35], v[178:181], v[198:201], v[32:35]
	v_mfma_f32_16x16x32_bf16 v[20:23], v[170:173], v[206:209], v[20:23]
	v_mfma_f32_16x16x32_bf16 v[16:19], v[178:181], v[206:209], v[16:19]
	v_mfma_f32_16x16x32_bf16 v[4:7], v[170:173], v[214:217], v[4:7]
	v_mfma_f32_16x16x32_bf16 v[0:3], v[178:181], v[214:217], v[0:3]
	v_mfma_f32_16x16x32_bf16 v[52:55], v[174:177], v[194:197], v[52:55]
	v_mfma_f32_16x16x32_bf16 v[48:51], v[182:185], v[194:197], v[48:51]
	v_mfma_f32_16x16x32_bf16 v[36:39], v[174:177], v[202:205], v[36:39]
	v_mfma_f32_16x16x32_bf16 v[32:35], v[182:185], v[202:205], v[32:35]
	v_mfma_f32_16x16x32_bf16 v[20:23], v[174:177], v[210:213], v[20:23]
	v_mfma_f32_16x16x32_bf16 v[16:19], v[182:185], v[210:213], v[16:19]
	v_mfma_f32_16x16x32_bf16 v[4:7], v[174:177], v[218:221], v[4:7]
	v_mfma_f32_16x16x32_bf16 v[0:3], v[182:185], v[218:221], v[0:3]
	s_setprio 0
	s_barrier
	s_add_i32 s51, s51, 2
	s_add_u32 s26, s26, 0x100
	s_addc_u32 s27, s27, 0
	s_add_u32 s49, s49, 0x100
	s_addc_u32 s50, s50, 0
	s_cmp_gt_u32 s51, 13
	s_cbranch_scc0 .LBB0_974
	s_and_b64 vcc, exec, s[10:11]
	s_cbranch_vccz .LBB0_977
	s_barrier

.LBB0_1055:
	s_add_u32 s16, s14, 0x100
	s_addc_u32 s17, s15, 0
	s_cmp_eq_u32 s39, 40
	s_cselect_b32 s21, s5, s17
	s_cselect_b32 s20, s4, s16
	s_cselect_b32 s19, s13, s38
	s_cselect_b32 s18, s12, s37
	v_lshl_add_u64 v[210:211], s[14:15], 0, v[134:135]
	s_add_i32 m0, s23, 0xc000
	s_nop 0
	global_load_lds_dwordx4 v[210:211], off
	v_lshl_add_u64 v[210:211], s[14:15], 0, v[136:137]
	s_add_i32 m0, s23, 0xe000
	s_nop 0
	global_load_lds_dwordx4 v[210:211], off
	ds_read_b128 v[142:145], v147
	ds_read_b128 v[150:153], v147 offset:1024
	ds_read_b128 v[154:157], v147 offset:2048
	ds_read_b128 v[158:161], v147 offset:3072
	ds_read_b128 v[162:165], v148
	ds_read_b128 v[166:169], v148 offset:1024
	ds_read_b128 v[170:173], v148 offset:2048
	ds_read_b128 v[174:177], v148 offset:3072
	ds_read_b128 v[178:181], v149
	ds_read_b128 v[182:185], v149 offset:1024
	ds_read_b128 v[186:189], v149 offset:2048
	ds_read_b128 v[190:193], v149 offset:3072
	ds_read_b128 v[194:197], v149 offset:4096
	ds_read_b128 v[198:201], v149 offset:5120
	ds_read_b128 v[202:205], v149 offset:6144
	ds_read_b128 v[206:209], v149 offset:7168
	s_waitcnt vmcnt(8)
	s_waitcnt lgkmcnt(0)
	s_barrier
	s_setprio 1
	s_waitcnt lgkmcnt(0)
	v_mfma_f32_16x16x32_bf16 v[124:127], v[142:145], v[178:181], v[124:127]
	v_mfma_f32_16x16x32_bf16 v[120:123], v[154:157], v[178:181], v[120:123]
	v_mfma_f32_16x16x32_bf16 v[108:111], v[142:145], v[186:189], v[108:111]
	v_mfma_f32_16x16x32_bf16 v[104:107], v[154:157], v[186:189], v[104:107]
	v_mfma_f32_16x16x32_bf16 v[92:95], v[142:145], v[194:197], v[92:95]
	v_mfma_f32_16x16x32_bf16 v[88:91], v[154:157], v[194:197], v[88:91]
	v_mfma_f32_16x16x32_bf16 v[76:79], v[142:145], v[202:205], v[76:79]
	v_mfma_f32_16x16x32_bf16 v[72:75], v[154:157], v[202:205], v[72:75]
	v_mfma_f32_16x16x32_bf16 v[124:127], v[150:153], v[182:185], v[124:127]
	v_mfma_f32_16x16x32_bf16 v[120:123], v[158:161], v[182:185], v[120:123]
	v_mfma_f32_16x16x32_bf16 v[108:111], v[150:153], v[190:193], v[108:111]
	v_mfma_f32_16x16x32_bf16 v[104:107], v[158:161], v[190:193], v[104:107]
	v_mfma_f32_16x16x32_bf16 v[92:95], v[150:153], v[198:201], v[92:95]
	v_mfma_f32_16x16x32_bf16 v[88:91], v[158:161], v[198:201], v[88:91]
	v_mfma_f32_16x16x32_bf16 v[76:79], v[150:153], v[206:209], v[76:79]
	v_mfma_f32_16x16x32_bf16 v[72:75], v[158:161], v[206:209], v[72:75]
	s_setprio 0
	s_setprio 1
	v_mfma_f32_16x16x32_bf16 v[116:119], v[162:165], v[178:181], v[116:119]
	v_mfma_f32_16x16x32_bf16 v[112:115], v[170:173], v[178:181], v[112:115]
	v_mfma_f32_16x16x32_bf16 v[100:103], v[162:165], v[186:189], v[100:103]
	v_mfma_f32_16x16x32_bf16 v[96:99], v[170:173], v[186:189], v[96:99]
	v_mfma_f32_16x16x32_bf16 v[84:87], v[162:165], v[194:197], v[84:87]
	v_mfma_f32_16x16x32_bf16 v[80:83], v[170:173], v[194:197], v[80:83]
	v_mfma_f32_16x16x32_bf16 v[68:71], v[162:165], v[202:205], v[68:71]
	v_mfma_f32_16x16x32_bf16 v[64:67], v[170:173], v[202:205], v[64:67]
	v_mfma_f32_16x16x32_bf16 v[116:119], v[166:169], v[182:185], v[116:119]
	v_mfma_f32_16x16x32_bf16 v[112:115], v[174:177], v[182:185], v[112:115]
	v_mfma_f32_16x16x32_bf16 v[100:103], v[166:169], v[190:193], v[100:103]
	v_mfma_f32_16x16x32_bf16 v[96:99], v[174:177], v[190:193], v[96:99]
	v_mfma_f32_16x16x32_bf16 v[84:87], v[166:169], v[198:201], v[84:87]
	v_mfma_f32_16x16x32_bf16 v[80:83], v[174:177], v[198:201], v[80:83]
	v_mfma_f32_16x16x32_bf16 v[68:71], v[166:169], v[206:209], v[68:71]
	v_mfma_f32_16x16x32_bf16 v[64:67], v[174:177], v[206:209], v[64:67]
	s_setprio 0
	s_barrier
	s_add_i32 s14, s30, s22
	v_lshl_add_u64 v[210:211], s[18:19], 0, v[130:131]
	s_mov_b32 m0, s14
	global_load_lds_dwordx4 v[210:211], off
	s_add_i32 m0, s14, 0x2000
	s_add_u32 s14, s18, 0xb0000
	v_lshl_add_u64 v[212:213], s[18:19], 0, v[128:129]
	s_addc_u32 s15, s19, 0
	s_add_i32 s40, s31, s22
	global_load_lds_dwordx4 v[212:213], off
	v_lshl_add_u64 v[214:215], s[14:15], 0, v[130:131]
	s_mov_b32 m0, s40
	v_lshl_add_u64 v[216:217], s[20:21], 0, v[128:129]
	global_load_lds_dwordx4 v[214:215], off
	v_lshl_add_u64 v[214:215], s[14:15], 0, v[128:129]
	s_add_i32 m0, s40, 0x2000
	s_nop 0
	global_load_lds_dwordx4 v[214:215], off
	v_lshl_add_u64 v[214:215], s[20:21], 0, v[130:131]
	s_mov_b32 m0, s23
	s_nop 0
	global_load_lds_dwordx4 v[214:215], off
	s_mov_b32 m0, s24
	s_nop 0
	global_load_lds_dwordx4 v[216:217], off
	ds_read_b128 v[178:181], v149 offset:16384
	ds_read_b128 v[182:185], v149 offset:17408
	ds_read_b128 v[186:189], v149 offset:18432
	ds_read_b128 v[190:193], v149 offset:19456
	ds_read_b128 v[194:197], v149 offset:20480
	ds_read_b128 v[198:201], v149 offset:21504
	ds_read_b128 v[202:205], v149 offset:22528
	ds_read_b128 v[206:209], v149 offset:23552
	s_waitcnt vmcnt(8)
	s_waitcnt lgkmcnt(0)
	s_barrier
	s_setprio 1
	s_waitcnt lgkmcnt(0)
	v_mfma_f32_16x16x32_bf16 v[60:63], v[142:145], v[178:181], v[60:63]
	v_mfma_f32_16x16x32_bf16 v[56:59], v[154:157], v[178:181], v[56:59]
	v_mfma_f32_16x16x32_bf16 v[44:47], v[142:145], v[186:189], v[44:47]
	v_mfma_f32_16x16x32_bf16 v[40:43], v[154:157], v[186:189], v[40:43]
	v_mfma_f32_16x16x32_bf16 v[28:31], v[142:145], v[194:197], v[28:31]
	v_mfma_f32_16x16x32_bf16 v[24:27], v[154:157], v[194:197], v[24:27]
	v_mfma_f32_16x16x32_bf16 v[12:15], v[142:145], v[202:205], v[12:15]
	v_mfma_f32_16x16x32_bf16 v[8:11], v[154:157], v[202:205], v[8:11]
	v_mfma_f32_16x16x32_bf16 v[60:63], v[150:153], v[182:185], v[60:63]
	v_mfma_f32_16x16x32_bf16 v[56:59], v[158:161], v[182:185], v[56:59]
	v_mfma_f32_16x16x32_bf16 v[44:47], v[150:153], v[190:193], v[44:47]
	v_mfma_f32_16x16x32_bf16 v[40:43], v[158:161], v[190:193], v[40:43]
	v_mfma_f32_16x16x32_bf16 v[28:31], v[150:153], v[198:201], v[28:31]
	v_mfma_f32_16x16x32_bf16 v[24:27], v[158:161], v[198:201], v[24:27]
	v_mfma_f32_16x16x32_bf16 v[12:15], v[150:153], v[206:209], v[12:15]
	v_mfma_f32_16x16x32_bf16 v[8:11], v[158:161], v[206:209], v[8:11]
	s_setprio 0
	s_setprio 1
	v_mfma_f32_16x16x32_bf16 v[52:55], v[162:165], v[178:181], v[52:55]
	v_mfma_f32_16x16x32_bf16 v[48:51], v[170:173], v[178:181], v[48:51]
	v_mfma_f32_16x16x32_bf16 v[36:39], v[162:165], v[186:189], v[36:39]
	v_mfma_f32_16x16x32_bf16 v[32:35], v[170:173], v[186:189], v[32:35]
	v_mfma_f32_16x16x32_bf16 v[20:23], v[162:165], v[194:197], v[20:23]
	v_mfma_f32_16x16x32_bf16 v[16:19], v[170:173], v[194:197], v[16:19]
	v_mfma_f32_16x16x32_bf16 v[4:7], v[162:165], v[202:205], v[4:7]
	v_mfma_f32_16x16x32_bf16 v[0:3], v[170:173], v[202:205], v[0:3]
	v_mfma_f32_16x16x32_bf16 v[52:55], v[166:169], v[182:185], v[52:55]
	v_mfma_f32_16x16x32_bf16 v[48:51], v[174:177], v[182:185], v[48:51]
	v_mfma_f32_16x16x32_bf16 v[36:39], v[166:169], v[190:193], v[36:39]
	v_mfma_f32_16x16x32_bf16 v[32:35], v[174:177], v[190:193], v[32:35]
	v_mfma_f32_16x16x32_bf16 v[20:23], v[166:169], v[198:201], v[20:23]
	v_mfma_f32_16x16x32_bf16 v[16:19], v[174:177], v[198:201], v[16:19]
	v_mfma_f32_16x16x32_bf16 v[4:7], v[166:169], v[206:209], v[4:7]
	v_mfma_f32_16x16x32_bf16 v[0:3], v[174:177], v[206:209], v[0:3]
	s_setprio 0
	s_barrier
	s_add_i32 s40, 0, 0x18000
	s_add_i32 s41, 0, 0x1c000
	v_add_u32_e32 v158, s40, v146
	v_add_u32_e32 v174, s41, v146
	s_add_u32 s14, s20, 0xb0000
	s_addc_u32 s15, s21, 0
	s_mov_b32 m0, s25
	v_lshl_add_u64 v[218:219], s[14:15], 0, v[130:131]
	global_load_lds_dwordx4 v[218:219], off
	v_lshl_add_u64 v[218:219], s[14:15], 0, v[128:129]
	s_mov_b32 m0, s26
	s_nop 0
	global_load_lds_dwordx4 v[218:219], off
	ds_read_b128 v[142:145], v158
	ds_read_b128 v[150:153], v158 offset:1024
	ds_read_b128 v[154:157], v158 offset:2048
	ds_read_b128 v[158:161], v158 offset:3072
	ds_read_b128 v[162:165], v174
	ds_read_b128 v[166:169], v174 offset:1024
	ds_read_b128 v[170:173], v174 offset:2048
	ds_read_b128 v[174:177], v174 offset:3072
	ds_read_b128 v[178:181], v149 offset:32768
	ds_read_b128 v[182:185], v149 offset:33792
	ds_read_b128 v[186:189], v149 offset:34816
	ds_read_b128 v[190:193], v149 offset:35840
	ds_read_b128 v[194:197], v149 offset:36864
	ds_read_b128 v[198:201], v149 offset:37888
	ds_read_b128 v[202:205], v149 offset:38912
	ds_read_b128 v[206:209], v149 offset:39936
	s_waitcnt vmcnt(8)
	s_waitcnt lgkmcnt(0)
	s_barrier
	s_setprio 1
	s_waitcnt lgkmcnt(0)
	v_mfma_f32_16x16x32_bf16 v[124:127], v[142:145], v[178:181], v[124:127]
	v_mfma_f32_16x16x32_bf16 v[120:123], v[154:157], v[178:181], v[120:123]
	v_mfma_f32_16x16x32_bf16 v[108:111], v[142:145], v[186:189], v[108:111]
	v_mfma_f32_16x16x32_bf16 v[104:107], v[154:157], v[186:189], v[104:107]
	v_mfma_f32_16x16x32_bf16 v[92:95], v[142:145], v[194:197], v[92:95]
	v_mfma_f32_16x16x32_bf16 v[88:91], v[154:157], v[194:197], v[88:91]
	v_mfma_f32_16x16x32_bf16 v[76:79], v[142:145], v[202:205], v[76:79]
	v_mfma_f32_16x16x32_bf16 v[72:75], v[154:157], v[202:205], v[72:75]
	v_mfma_f32_16x16x32_bf16 v[124:127], v[150:153], v[182:185], v[124:127]
	v_mfma_f32_16x16x32_bf16 v[120:123], v[158:161], v[182:185], v[120:123]
	v_mfma_f32_16x16x32_bf16 v[108:111], v[150:153], v[190:193], v[108:111]
	v_mfma_f32_16x16x32_bf16 v[104:107], v[158:161], v[190:193], v[104:107]
	v_mfma_f32_16x16x32_bf16 v[92:95], v[150:153], v[198:201], v[92:95]
	v_mfma_f32_16x16x32_bf16 v[88:91], v[158:161], v[198:201], v[88:91]
	v_mfma_f32_16x16x32_bf16 v[76:79], v[150:153], v[206:209], v[76:79]
	v_mfma_f32_16x16x32_bf16 v[72:75], v[158:161], v[206:209], v[72:75]
	s_setprio 0
	s_setprio 1
	v_mfma_f32_16x16x32_bf16 v[116:119], v[162:165], v[178:181], v[116:119]
	v_mfma_f32_16x16x32_bf16 v[112:115], v[170:173], v[178:181], v[112:115]
	v_mfma_f32_16x16x32_bf16 v[100:103], v[162:165], v[186:189], v[100:103]
	v_mfma_f32_16x16x32_bf16 v[96:99], v[170:173], v[186:189], v[96:99]
	v_mfma_f32_16x16x32_bf16 v[84:87], v[162:165], v[194:197], v[84:87]
	v_mfma_f32_16x16x32_bf16 v[80:83], v[170:173], v[194:197], v[80:83]
	v_mfma_f32_16x16x32_bf16 v[68:71], v[162:165], v[202:205], v[68:71]
	v_mfma_f32_16x16x32_bf16 v[64:67], v[170:173], v[202:205], v[64:67]
	v_mfma_f32_16x16x32_bf16 v[116:119], v[166:169], v[182:185], v[116:119]
	v_mfma_f32_16x16x32_bf16 v[112:115], v[174:177], v[182:185], v[112:115]
	v_mfma_f32_16x16x32_bf16 v[100:103], v[166:169], v[190:193], v[100:103]
	v_mfma_f32_16x16x32_bf16 v[96:99], v[174:177], v[190:193], v[96:99]
	v_mfma_f32_16x16x32_bf16 v[84:87], v[166:169], v[198:201], v[84:87]
	v_mfma_f32_16x16x32_bf16 v[80:83], v[174:177], v[198:201], v[80:83]
	v_mfma_f32_16x16x32_bf16 v[68:71], v[166:169], v[206:209], v[68:71]
	v_mfma_f32_16x16x32_bf16 v[64:67], v[174:177], v[206:209], v[64:67]
	s_setprio 0
	s_barrier
	s_add_i32 s14, s40, s22
	v_lshl_add_u64 v[210:211], v[210:211], 0, s[8:9]
	s_mov_b32 m0, s14
	global_load_lds_dwordx4 v[210:211], off
	s_add_i32 m0, s14, 0x2000
	s_add_u32 s14, s18, 0xb0080
	v_lshl_add_u64 v[210:211], v[212:213], 0, s[8:9]
	s_addc_u32 s15, s19, 0
	s_add_i32 s18, s41, s22
	global_load_lds_dwordx4 v[210:211], off
	v_lshl_add_u64 v[210:211], s[14:15], 0, v[130:131]
	s_mov_b32 m0, s18
	s_nop 0
	global_load_lds_dwordx4 v[210:211], off
	v_lshl_add_u64 v[210:211], s[14:15], 0, v[128:129]
	s_add_i32 m0, s18, 0x2000
	s_nop 0
	global_load_lds_dwordx4 v[210:211], off
	v_lshl_add_u64 v[210:211], v[214:215], 0, s[8:9]
	s_mov_b32 m0, s27
	s_nop 0
	global_load_lds_dwordx4 v[210:211], off
	v_lshl_add_u64 v[210:211], v[216:217], 0, s[8:9]
	s_mov_b32 m0, s28
	s_nop 0
	global_load_lds_dwordx4 v[210:211], off
	ds_read_b128 v[178:181], v149 offset:49152
	ds_read_b128 v[182:185], v149 offset:50176
	ds_read_b128 v[186:189], v149 offset:51200
	ds_read_b128 v[190:193], v149 offset:52224
	ds_read_b128 v[194:197], v149 offset:53248
	ds_read_b128 v[198:201], v149 offset:54272
	ds_read_b128 v[202:205], v149 offset:55296
	ds_read_b128 v[206:209], v149 offset:56320
	s_waitcnt vmcnt(8)
	s_waitcnt lgkmcnt(0)
	s_barrier
	s_setprio 1
	s_waitcnt lgkmcnt(0)
	v_mfma_f32_16x16x32_bf16 v[60:63], v[142:145], v[178:181], v[60:63]
	v_mfma_f32_16x16x32_bf16 v[56:59], v[154:157], v[178:181], v[56:59]
	v_mfma_f32_16x16x32_bf16 v[44:47], v[142:145], v[186:189], v[44:47]
	v_mfma_f32_16x16x32_bf16 v[40:43], v[154:157], v[186:189], v[40:43]
	v_mfma_f32_16x16x32_bf16 v[28:31], v[142:145], v[194:197], v[28:31]
	v_mfma_f32_16x16x32_bf16 v[24:27], v[154:157], v[194:197], v[24:27]
	v_mfma_f32_16x16x32_bf16 v[12:15], v[142:145], v[202:205], v[12:15]
	v_mfma_f32_16x16x32_bf16 v[8:11], v[154:157], v[202:205], v[8:11]
	v_mfma_f32_16x16x32_bf16 v[60:63], v[150:153], v[182:185], v[60:63]
	v_mfma_f32_16x16x32_bf16 v[56:59], v[158:161], v[182:185], v[56:59]
	v_mfma_f32_16x16x32_bf16 v[44:47], v[150:153], v[190:193], v[44:47]
	v_mfma_f32_16x16x32_bf16 v[40:43], v[158:161], v[190:193], v[40:43]
	v_mfma_f32_16x16x32_bf16 v[28:31], v[150:153], v[198:201], v[28:31]
	v_mfma_f32_16x16x32_bf16 v[24:27], v[158:161], v[198:201], v[24:27]
	v_mfma_f32_16x16x32_bf16 v[12:15], v[150:153], v[206:209], v[12:15]
	v_mfma_f32_16x16x32_bf16 v[8:11], v[158:161], v[206:209], v[8:11]
	s_setprio 0
	s_setprio 1
	v_mfma_f32_16x16x32_bf16 v[52:55], v[162:165], v[178:181], v[52:55]
	v_mfma_f32_16x16x32_bf16 v[48:51], v[170:173], v[178:181], v[48:51]
	v_mfma_f32_16x16x32_bf16 v[36:39], v[162:165], v[186:189], v[36:39]
	v_mfma_f32_16x16x32_bf16 v[32:35], v[170:173], v[186:189], v[32:35]
	v_mfma_f32_16x16x32_bf16 v[20:23], v[162:165], v[194:197], v[20:23]
	v_mfma_f32_16x16x32_bf16 v[16:19], v[170:173], v[194:197], v[16:19]
	v_mfma_f32_16x16x32_bf16 v[4:7], v[162:165], v[202:205], v[4:7]
	v_mfma_f32_16x16x32_bf16 v[0:3], v[170:173], v[202:205], v[0:3]
	v_mfma_f32_16x16x32_bf16 v[52:55], v[166:169], v[182:185], v[52:55]
	v_mfma_f32_16x16x32_bf16 v[48:51], v[174:177], v[182:185], v[48:51]
	v_mfma_f32_16x16x32_bf16 v[36:39], v[166:169], v[190:193], v[36:39]
	v_mfma_f32_16x16x32_bf16 v[32:35], v[174:177], v[190:193], v[32:35]
	v_mfma_f32_16x16x32_bf16 v[20:23], v[166:169], v[198:201], v[20:23]
	v_mfma_f32_16x16x32_bf16 v[16:19], v[174:177], v[198:201], v[16:19]
	v_mfma_f32_16x16x32_bf16 v[4:7], v[166:169], v[206:209], v[4:7]
	v_mfma_f32_16x16x32_bf16 v[0:3], v[174:177], v[206:209], v[0:3]
	s_setprio 0
	s_barrier
	s_add_i32 s39, s39, 2
	s_add_u32 s37, s37, 0x100
	s_addc_u32 s38, s38, 0
	s_cmp_gt_u32 s39, 41
	s_mov_b64 s[14:15], s[16:17]
	s_cbranch_scc0 .LBB0_1055
	s_and_b64 vcc, exec, s[10:11]
	s_cbranch_vccz .LBB0_1058
	s_barrier
